# LN passes rewritten by hand: 3-row-deep counted-vmcnt pipeline, DPP row_bcast reduction, cvt_pk_bf16
# speedup vs baseline: 1.0037x; 1.0037x over previous
.LBB0_77:
	s_mov_b64 s[10:11], 0
	s_mov_b64 s[18:19], -1
	s_mov_b64 s[16:17], 0
	s_cmp_lt_i32 s2, 1
	s_mov_b64 s[0:1], 0
	s_cbranch_scc1 .LBB0_86
	s_cmp_eq_u32 s2, 1
	s_mov_b64 s[0:1], -1
	s_cbranch_scc0 .LBB0_85
	s_waitcnt vmcnt(0)
	v_readlane_b32 s2, v254, 38
	v_lshrrev_b32_e32 v146, 6, v221
	v_and_b32_e32 v112, 63, v221
	v_mov_b32_e32 v150, 0x800000
	v_mov_b32_e32 v151, 0
	v_mov_b32_e32 v152, 0x400000
	v_mov_b32_e32 v153, 0
	v_mov_b32_e32 v154, 0x3000
	v_mov_b32_e32 v155, 0
	v_add_u32_e32 v146, s2, v146
	v_lshlrev_b32_e32 v148, 4, v112
	v_mov_b32_e32 v149, 0
	v_lshl_add_u32 v140, v146, 12, v148
	v_mov_b32_e32 v141, 0
	v_mov_b32_e32 v142, 0xba800000
	s_mov_b32 s0, 0
	v_add_u32_e32 v114, 0x1000, v148
	v_mov_b32_e32 v115, 0
	v_lshl_add_u64 v[134:135], s[60:61], 0, v[114:115]
	v_lshlrev_b32_e32 v114, 3, v112
	v_lshl_add_u32 v114, v146, 11, v114
	s_add_u32 s18, s60, 0x3100000
	s_addc_u32 s19, s61, 0
	v_lshl_add_u64 v[132:133], s[18:19], 0, v[114:115]
	v_lshl_add_u64 v[128:129], s[68:69], 0, v[140:141]
	global_load_dwordx4 v[0:3], v[128:129], off nt
	global_load_dwordx4 v[4:7], v[128:129], off offset:1024 nt
	global_load_dwordx4 v[8:11], v[128:129], off offset:2048 nt
	global_load_dwordx4 v[12:15], v[128:129], off offset:3072 nt
	v_lshl_add_u64 v[128:129], v[128:129], 0, v[150:151]
	global_load_dword v156, v[134:135], off
	global_load_dword v156, v[134:135], off
	global_load_dword v156, v[134:135], off
	global_load_dword v156, v[134:135], off
	global_load_dwordx4 v[16:19], v[128:129], off nt
	global_load_dwordx4 v[20:23], v[128:129], off offset:1024 nt
	global_load_dwordx4 v[24:27], v[128:129], off offset:2048 nt
	global_load_dwordx4 v[28:31], v[128:129], off offset:3072 nt
	v_lshl_add_u64 v[128:129], s[70:71], 0, v[140:141]
	global_load_dword v156, v[134:135], off
	global_load_dword v156, v[134:135], off
	global_load_dword v156, v[134:135], off
	global_load_dword v156, v[134:135], off
.Lln0_loop:
	global_load_dwordx4 v[48:51], v[134:135], off offset:-4096
	global_load_dwordx4 v[52:55], v[134:135], off offset:-3072
	global_load_dwordx4 v[56:59], v[134:135], off offset:-2048
	global_load_dwordx4 v[60:63], v[134:135], off offset:-1024
	global_load_dwordx4 v[64:67], v[134:135], off
	global_load_dwordx4 v[68:71], v[134:135], off offset:1024
	global_load_dwordx4 v[72:75], v[134:135], off offset:2048
	global_load_dwordx4 v[76:79], v[134:135], off offset:3072
	v_lshl_add_u64 v[134:135], v[134:135], 0, v[154:155]
	global_load_dwordx4 v[32:35], v[128:129], off nt
	global_load_dwordx4 v[36:39], v[128:129], off offset:1024 nt
	global_load_dwordx4 v[40:43], v[128:129], off offset:2048 nt
	global_load_dwordx4 v[44:47], v[128:129], off offset:3072 nt
	v_lshl_add_u64 v[128:129], v[128:129], 0, v[150:151]
	s_waitcnt vmcnt(24)
	v_add_f32_e32 v112, v0, v1
	v_add_f32_e32 v113, v2, v3
	v_add_f32_e32 v114, v4, v5
	v_add_f32_e32 v115, v6, v7
	v_add_f32_e32 v116, v8, v9
	v_add_f32_e32 v117, v10, v11
	v_add_f32_e32 v118, v12, v13
	v_add_f32_e32 v119, v14, v15
	v_add_f32_e32 v112, v112, v116
	v_add_f32_e32 v113, v113, v117
	v_add_f32_e32 v114, v114, v118
	v_add_f32_e32 v115, v115, v119
	v_add_f32_e32 v112, v112, v113
	v_add_f32_e32 v114, v114, v115
	v_add_f32_e32 v112, v112, v114
	s_nop 1
	v_add_f32_dpp v112, v112, v112 quad_perm:[1,0,3,2] row_mask:0xf bank_mask:0xf
	s_nop 1
	v_add_f32_dpp v112, v112, v112 quad_perm:[2,3,0,1] row_mask:0xf bank_mask:0xf
	s_nop 1
	v_add_f32_dpp v112, v112, v112 row_half_mirror row_mask:0xf bank_mask:0xf
	s_nop 1
	v_add_f32_dpp v112, v112, v112 row_mirror row_mask:0xf bank_mask:0xf
	s_nop 1
	v_add_f32_dpp v112, v112, v112 row_bcast:15 row_mask:0xa bank_mask:0xf
	s_nop 1
	v_add_f32_dpp v112, v112, v112 row_bcast:31 row_mask:0xc bank_mask:0xf
	s_nop 1
	v_readlane_b32 s2, v112, 63
	s_nop 1
	v_fmac_f32_e32 v0, s2, v142
	v_fmac_f32_e32 v1, s2, v142
	v_fmac_f32_e32 v2, s2, v142
	v_fmac_f32_e32 v3, s2, v142
	v_fmac_f32_e32 v4, s2, v142
	v_fmac_f32_e32 v5, s2, v142
	v_fmac_f32_e32 v6, s2, v142
	v_fmac_f32_e32 v7, s2, v142
	v_fmac_f32_e32 v8, s2, v142
	v_fmac_f32_e32 v9, s2, v142
	v_fmac_f32_e32 v10, s2, v142
	v_fmac_f32_e32 v11, s2, v142
	v_fmac_f32_e32 v12, s2, v142
	v_fmac_f32_e32 v13, s2, v142
	v_fmac_f32_e32 v14, s2, v142
	v_fmac_f32_e32 v15, s2, v142
	v_mul_f32_e32 v112, v0, v0
	v_mul_f32_e32 v113, v1, v1
	v_mul_f32_e32 v114, v2, v2
	v_mul_f32_e32 v115, v3, v3
	v_fmac_f32_e32 v112, v4, v4
	v_fmac_f32_e32 v113, v5, v5
	v_fmac_f32_e32 v114, v6, v6
	v_fmac_f32_e32 v115, v7, v7
	v_fmac_f32_e32 v112, v8, v8
	v_fmac_f32_e32 v113, v9, v9
	v_fmac_f32_e32 v114, v10, v10
	v_fmac_f32_e32 v115, v11, v11
	v_fmac_f32_e32 v112, v12, v12
	v_fmac_f32_e32 v113, v13, v13
	v_fmac_f32_e32 v114, v14, v14
	v_fmac_f32_e32 v115, v15, v15
	v_add_f32_e32 v112, v112, v113
	v_add_f32_e32 v114, v114, v115
	v_add_f32_e32 v112, v112, v114
	s_nop 1
	v_add_f32_dpp v112, v112, v112 quad_perm:[1,0,3,2] row_mask:0xf bank_mask:0xf
	s_nop 1
	v_add_f32_dpp v112, v112, v112 quad_perm:[2,3,0,1] row_mask:0xf bank_mask:0xf
	s_nop 1
	v_add_f32_dpp v112, v112, v112 row_half_mirror row_mask:0xf bank_mask:0xf
	s_nop 1
	v_add_f32_dpp v112, v112, v112 row_mirror row_mask:0xf bank_mask:0xf
	s_nop 1
	v_add_f32_dpp v112, v112, v112 row_bcast:15 row_mask:0xa bank_mask:0xf
	s_nop 1
	v_add_f32_dpp v112, v112, v112 row_bcast:31 row_mask:0xc bank_mask:0xf
	s_nop 1
	v_readlane_b32 s2, v112, 63
	s_nop 1
	v_mov_b32_e32 v113, 0x358637bd
	v_mov_b32_e32 v114, 0x3a800000
	v_fmac_f32_e32 v113, s2, v114
	v_rsq_f32_e32 v115, v113
	v_mul_f32_e32 v113, 0.5, v113
	v_mul_f32_e32 v116, v115, v115
	v_mov_b32_e32 v117, 0x3fc00000
	v_fma_f32 v116, -v113, v116, v117
	v_mul_f32_e32 v144, v115, v116
	v_pk_mul_f32 v[0:1], v[0:1], v[144:145] op_sel_hi:[1,0]
	v_pk_mul_f32 v[2:3], v[2:3], v[144:145] op_sel_hi:[1,0]
	v_pk_mul_f32 v[4:5], v[4:5], v[144:145] op_sel_hi:[1,0]
	v_pk_mul_f32 v[6:7], v[6:7], v[144:145] op_sel_hi:[1,0]
	v_pk_mul_f32 v[8:9], v[8:9], v[144:145] op_sel_hi:[1,0]
	v_pk_mul_f32 v[10:11], v[10:11], v[144:145] op_sel_hi:[1,0]
	v_pk_mul_f32 v[12:13], v[12:13], v[144:145] op_sel_hi:[1,0]
	v_pk_mul_f32 v[14:15], v[14:15], v[144:145] op_sel_hi:[1,0]
	s_waitcnt vmcnt(4)
	v_pk_add_f32 v[64:65], v[64:65], 1.0 op_sel_hi:[1,0]
	v_pk_add_f32 v[66:67], v[66:67], 1.0 op_sel_hi:[1,0]
	v_pk_add_f32 v[68:69], v[68:69], 1.0 op_sel_hi:[1,0]
	v_pk_add_f32 v[70:71], v[70:71], 1.0 op_sel_hi:[1,0]
	v_pk_add_f32 v[72:73], v[72:73], 1.0 op_sel_hi:[1,0]
	v_pk_add_f32 v[74:75], v[74:75], 1.0 op_sel_hi:[1,0]
	v_pk_add_f32 v[76:77], v[76:77], 1.0 op_sel_hi:[1,0]
	v_pk_add_f32 v[78:79], v[78:79], 1.0 op_sel_hi:[1,0]
	v_pk_fma_f32 v[0:1], v[64:65], v[0:1], v[48:49]
	v_pk_fma_f32 v[2:3], v[66:67], v[2:3], v[50:51]
	v_pk_fma_f32 v[4:5], v[68:69], v[4:5], v[52:53]
	v_pk_fma_f32 v[6:7], v[70:71], v[6:7], v[54:55]
	v_pk_fma_f32 v[8:9], v[72:73], v[8:9], v[56:57]
	v_pk_fma_f32 v[10:11], v[74:75], v[10:11], v[58:59]
	v_pk_fma_f32 v[12:13], v[76:77], v[12:13], v[60:61]
	v_pk_fma_f32 v[14:15], v[78:79], v[14:15], v[62:63]
	v_cvt_pk_bf16_f32 v120, v0, v1
	v_cvt_pk_bf16_f32 v121, v2, v3
	v_cvt_pk_bf16_f32 v122, v4, v5
	v_cvt_pk_bf16_f32 v123, v6, v7
	v_cvt_pk_bf16_f32 v124, v8, v9
	v_cvt_pk_bf16_f32 v125, v10, v11
	v_cvt_pk_bf16_f32 v126, v12, v13
	v_cvt_pk_bf16_f32 v127, v14, v15
	global_store_dwordx2 v[132:133], v[120:121], off
	global_store_dwordx2 v[132:133], v[122:123], off offset:512
	global_store_dwordx2 v[132:133], v[124:125], off offset:1024
	global_store_dwordx2 v[132:133], v[126:127], off offset:1536
	v_lshl_add_u64 v[132:133], v[132:133], 0, v[152:153]
	global_load_dwordx4 v[0:3], v[128:129], off nt
	global_load_dwordx4 v[4:7], v[128:129], off offset:1024 nt
	global_load_dwordx4 v[8:11], v[128:129], off offset:2048 nt
	global_load_dwordx4 v[12:15], v[128:129], off offset:3072 nt
	v_lshl_add_u64 v[128:129], v[128:129], 0, v[150:151]
	v_add_f32_e32 v112, v16, v17
	v_add_f32_e32 v113, v18, v19
	v_add_f32_e32 v114, v20, v21
	v_add_f32_e32 v115, v22, v23
	v_add_f32_e32 v116, v24, v25
	v_add_f32_e32 v117, v26, v27
	v_add_f32_e32 v118, v28, v29
	v_add_f32_e32 v119, v30, v31
	v_add_f32_e32 v112, v112, v116
	v_add_f32_e32 v113, v113, v117
	v_add_f32_e32 v114, v114, v118
	v_add_f32_e32 v115, v115, v119
	v_add_f32_e32 v112, v112, v113
	v_add_f32_e32 v114, v114, v115
	v_add_f32_e32 v112, v112, v114
	s_nop 1
	v_add_f32_dpp v112, v112, v112 quad_perm:[1,0,3,2] row_mask:0xf bank_mask:0xf
	s_nop 1
	v_add_f32_dpp v112, v112, v112 quad_perm:[2,3,0,1] row_mask:0xf bank_mask:0xf
	s_nop 1
	v_add_f32_dpp v112, v112, v112 row_half_mirror row_mask:0xf bank_mask:0xf
	s_nop 1
	v_add_f32_dpp v112, v112, v112 row_mirror row_mask:0xf bank_mask:0xf
	s_nop 1
	v_add_f32_dpp v112, v112, v112 row_bcast:15 row_mask:0xa bank_mask:0xf
	s_nop 1
	v_add_f32_dpp v112, v112, v112 row_bcast:31 row_mask:0xc bank_mask:0xf
	s_nop 1
	v_readlane_b32 s2, v112, 63
	s_nop 1
	v_fmac_f32_e32 v16, s2, v142
	v_fmac_f32_e32 v17, s2, v142
	v_fmac_f32_e32 v18, s2, v142
	v_fmac_f32_e32 v19, s2, v142
	v_fmac_f32_e32 v20, s2, v142
	v_fmac_f32_e32 v21, s2, v142
	v_fmac_f32_e32 v22, s2, v142
	v_fmac_f32_e32 v23, s2, v142
	v_fmac_f32_e32 v24, s2, v142
	v_fmac_f32_e32 v25, s2, v142
	v_fmac_f32_e32 v26, s2, v142
	v_fmac_f32_e32 v27, s2, v142
	v_fmac_f32_e32 v28, s2, v142
	v_fmac_f32_e32 v29, s2, v142
	v_fmac_f32_e32 v30, s2, v142
	v_fmac_f32_e32 v31, s2, v142
	v_mul_f32_e32 v112, v16, v16
	v_mul_f32_e32 v113, v17, v17
	v_mul_f32_e32 v114, v18, v18
	v_mul_f32_e32 v115, v19, v19
	v_fmac_f32_e32 v112, v20, v20
	v_fmac_f32_e32 v113, v21, v21
	v_fmac_f32_e32 v114, v22, v22
	v_fmac_f32_e32 v115, v23, v23
	v_fmac_f32_e32 v112, v24, v24
	v_fmac_f32_e32 v113, v25, v25
	v_fmac_f32_e32 v114, v26, v26
	v_fmac_f32_e32 v115, v27, v27
	v_fmac_f32_e32 v112, v28, v28
	v_fmac_f32_e32 v113, v29, v29
	v_fmac_f32_e32 v114, v30, v30
	v_fmac_f32_e32 v115, v31, v31
	v_add_f32_e32 v112, v112, v113
	v_add_f32_e32 v114, v114, v115
	v_add_f32_e32 v112, v112, v114
	s_nop 1
	v_add_f32_dpp v112, v112, v112 quad_perm:[1,0,3,2] row_mask:0xf bank_mask:0xf
	s_nop 1
	v_add_f32_dpp v112, v112, v112 quad_perm:[2,3,0,1] row_mask:0xf bank_mask:0xf
	s_nop 1
	v_add_f32_dpp v112, v112, v112 row_half_mirror row_mask:0xf bank_mask:0xf
	s_nop 1
	v_add_f32_dpp v112, v112, v112 row_mirror row_mask:0xf bank_mask:0xf
	s_nop 1
	v_add_f32_dpp v112, v112, v112 row_bcast:15 row_mask:0xa bank_mask:0xf
	s_nop 1
	v_add_f32_dpp v112, v112, v112 row_bcast:31 row_mask:0xc bank_mask:0xf
	s_nop 1
	v_readlane_b32 s2, v112, 63
	s_nop 1
	v_mov_b32_e32 v113, 0x358637bd
	v_mov_b32_e32 v114, 0x3a800000
	v_fmac_f32_e32 v113, s2, v114
	v_rsq_f32_e32 v115, v113
	v_mul_f32_e32 v113, 0.5, v113
	v_mul_f32_e32 v116, v115, v115
	v_mov_b32_e32 v117, 0x3fc00000
	v_fma_f32 v116, -v113, v116, v117
	v_mul_f32_e32 v144, v115, v116
	v_pk_mul_f32 v[16:17], v[16:17], v[144:145] op_sel_hi:[1,0]
	v_pk_mul_f32 v[18:19], v[18:19], v[144:145] op_sel_hi:[1,0]
	v_pk_mul_f32 v[20:21], v[20:21], v[144:145] op_sel_hi:[1,0]
	v_pk_mul_f32 v[22:23], v[22:23], v[144:145] op_sel_hi:[1,0]
	v_pk_mul_f32 v[24:25], v[24:25], v[144:145] op_sel_hi:[1,0]
	v_pk_mul_f32 v[26:27], v[26:27], v[144:145] op_sel_hi:[1,0]
	v_pk_mul_f32 v[28:29], v[28:29], v[144:145] op_sel_hi:[1,0]
	v_pk_mul_f32 v[30:31], v[30:31], v[144:145] op_sel_hi:[1,0]
	v_pk_fma_f32 v[16:17], v[64:65], v[16:17], v[48:49]
	v_pk_fma_f32 v[18:19], v[66:67], v[18:19], v[50:51]
	v_pk_fma_f32 v[20:21], v[68:69], v[20:21], v[52:53]
	v_pk_fma_f32 v[22:23], v[70:71], v[22:23], v[54:55]
	v_pk_fma_f32 v[24:25], v[72:73], v[24:25], v[56:57]
	v_pk_fma_f32 v[26:27], v[74:75], v[26:27], v[58:59]
	v_pk_fma_f32 v[28:29], v[76:77], v[28:29], v[60:61]
	v_pk_fma_f32 v[30:31], v[78:79], v[30:31], v[62:63]
	v_cvt_pk_bf16_f32 v120, v16, v17
	v_cvt_pk_bf16_f32 v121, v18, v19
	v_cvt_pk_bf16_f32 v122, v20, v21
	v_cvt_pk_bf16_f32 v123, v22, v23
	v_cvt_pk_bf16_f32 v124, v24, v25
	v_cvt_pk_bf16_f32 v125, v26, v27
	v_cvt_pk_bf16_f32 v126, v28, v29
	v_cvt_pk_bf16_f32 v127, v30, v31
	global_store_dwordx2 v[132:133], v[120:121], off
	global_store_dwordx2 v[132:133], v[122:123], off offset:512
	global_store_dwordx2 v[132:133], v[124:125], off offset:1024
	global_store_dwordx2 v[132:133], v[126:127], off offset:1536
	v_lshl_add_u64 v[132:133], v[132:133], 0, v[152:153]
	global_load_dwordx4 v[48:51], v[134:135], off offset:-4096
	global_load_dwordx4 v[52:55], v[134:135], off offset:-3072
	global_load_dwordx4 v[56:59], v[134:135], off offset:-2048
	global_load_dwordx4 v[60:63], v[134:135], off offset:-1024
	global_load_dwordx4 v[64:67], v[134:135], off
	global_load_dwordx4 v[68:71], v[134:135], off offset:1024
	global_load_dwordx4 v[72:75], v[134:135], off offset:2048
	global_load_dwordx4 v[76:79], v[134:135], off offset:3072
	v_lshl_add_u64 v[134:135], v[134:135], 0, v[154:155]
	global_load_dwordx4 v[16:19], v[128:129], off nt
	global_load_dwordx4 v[20:23], v[128:129], off offset:1024 nt
	global_load_dwordx4 v[24:27], v[128:129], off offset:2048 nt
	global_load_dwordx4 v[28:31], v[128:129], off offset:3072 nt
	v_lshl_add_u64 v[128:129], v[128:129], 0, v[150:151]
	s_waitcnt vmcnt(24)
	v_add_f32_e32 v112, v32, v33
	v_add_f32_e32 v113, v34, v35
	v_add_f32_e32 v114, v36, v37
	v_add_f32_e32 v115, v38, v39
	v_add_f32_e32 v116, v40, v41
	v_add_f32_e32 v117, v42, v43
	v_add_f32_e32 v118, v44, v45
	v_add_f32_e32 v119, v46, v47
	v_add_f32_e32 v112, v112, v116
	v_add_f32_e32 v113, v113, v117
	v_add_f32_e32 v114, v114, v118
	v_add_f32_e32 v115, v115, v119
	v_add_f32_e32 v112, v112, v113
	v_add_f32_e32 v114, v114, v115
	v_add_f32_e32 v112, v112, v114
	s_nop 1
	v_add_f32_dpp v112, v112, v112 quad_perm:[1,0,3,2] row_mask:0xf bank_mask:0xf
	s_nop 1
	v_add_f32_dpp v112, v112, v112 quad_perm:[2,3,0,1] row_mask:0xf bank_mask:0xf
	s_nop 1
	v_add_f32_dpp v112, v112, v112 row_half_mirror row_mask:0xf bank_mask:0xf
	s_nop 1
	v_add_f32_dpp v112, v112, v112 row_mirror row_mask:0xf bank_mask:0xf
	s_nop 1
	v_add_f32_dpp v112, v112, v112 row_bcast:15 row_mask:0xa bank_mask:0xf
	s_nop 1
	v_add_f32_dpp v112, v112, v112 row_bcast:31 row_mask:0xc bank_mask:0xf
	s_nop 1
	v_readlane_b32 s2, v112, 63
	s_nop 1
	v_fmac_f32_e32 v32, s2, v142
	v_fmac_f32_e32 v33, s2, v142
	v_fmac_f32_e32 v34, s2, v142
	v_fmac_f32_e32 v35, s2, v142
	v_fmac_f32_e32 v36, s2, v142
	v_fmac_f32_e32 v37, s2, v142
	v_fmac_f32_e32 v38, s2, v142
	v_fmac_f32_e32 v39, s2, v142
	v_fmac_f32_e32 v40, s2, v142
	v_fmac_f32_e32 v41, s2, v142
	v_fmac_f32_e32 v42, s2, v142
	v_fmac_f32_e32 v43, s2, v142
	v_fmac_f32_e32 v44, s2, v142
	v_fmac_f32_e32 v45, s2, v142
	v_fmac_f32_e32 v46, s2, v142
	v_fmac_f32_e32 v47, s2, v142
	v_mul_f32_e32 v112, v32, v32
	v_mul_f32_e32 v113, v33, v33
	v_mul_f32_e32 v114, v34, v34
	v_mul_f32_e32 v115, v35, v35
	v_fmac_f32_e32 v112, v36, v36
	v_fmac_f32_e32 v113, v37, v37
	v_fmac_f32_e32 v114, v38, v38
	v_fmac_f32_e32 v115, v39, v39
	v_fmac_f32_e32 v112, v40, v40
	v_fmac_f32_e32 v113, v41, v41
	v_fmac_f32_e32 v114, v42, v42
	v_fmac_f32_e32 v115, v43, v43
	v_fmac_f32_e32 v112, v44, v44
	v_fmac_f32_e32 v113, v45, v45
	v_fmac_f32_e32 v114, v46, v46
	v_fmac_f32_e32 v115, v47, v47
	v_add_f32_e32 v112, v112, v113
	v_add_f32_e32 v114, v114, v115
	v_add_f32_e32 v112, v112, v114
	s_nop 1
	v_add_f32_dpp v112, v112, v112 quad_perm:[1,0,3,2] row_mask:0xf bank_mask:0xf
	s_nop 1
	v_add_f32_dpp v112, v112, v112 quad_perm:[2,3,0,1] row_mask:0xf bank_mask:0xf
	s_nop 1
	v_add_f32_dpp v112, v112, v112 row_half_mirror row_mask:0xf bank_mask:0xf
	s_nop 1
	v_add_f32_dpp v112, v112, v112 row_mirror row_mask:0xf bank_mask:0xf
	s_nop 1
	v_add_f32_dpp v112, v112, v112 row_bcast:15 row_mask:0xa bank_mask:0xf
	s_nop 1
	v_add_f32_dpp v112, v112, v112 row_bcast:31 row_mask:0xc bank_mask:0xf
	s_nop 1
	v_readlane_b32 s2, v112, 63
	s_nop 1
	v_mov_b32_e32 v113, 0x358637bd
	v_mov_b32_e32 v114, 0x3a800000
	v_fmac_f32_e32 v113, s2, v114
	v_rsq_f32_e32 v115, v113
	v_mul_f32_e32 v113, 0.5, v113
	v_mul_f32_e32 v116, v115, v115
	v_mov_b32_e32 v117, 0x3fc00000
	v_fma_f32 v116, -v113, v116, v117
	v_mul_f32_e32 v144, v115, v116
	v_pk_mul_f32 v[32:33], v[32:33], v[144:145] op_sel_hi:[1,0]
	v_pk_mul_f32 v[34:35], v[34:35], v[144:145] op_sel_hi:[1,0]
	v_pk_mul_f32 v[36:37], v[36:37], v[144:145] op_sel_hi:[1,0]
	v_pk_mul_f32 v[38:39], v[38:39], v[144:145] op_sel_hi:[1,0]
	v_pk_mul_f32 v[40:41], v[40:41], v[144:145] op_sel_hi:[1,0]
	v_pk_mul_f32 v[42:43], v[42:43], v[144:145] op_sel_hi:[1,0]
	v_pk_mul_f32 v[44:45], v[44:45], v[144:145] op_sel_hi:[1,0]
	v_pk_mul_f32 v[46:47], v[46:47], v[144:145] op_sel_hi:[1,0]
	s_waitcnt vmcnt(4)
	v_pk_add_f32 v[64:65], v[64:65], 1.0 op_sel_hi:[1,0]
	v_pk_add_f32 v[66:67], v[66:67], 1.0 op_sel_hi:[1,0]
	v_pk_add_f32 v[68:69], v[68:69], 1.0 op_sel_hi:[1,0]
	v_pk_add_f32 v[70:71], v[70:71], 1.0 op_sel_hi:[1,0]
	v_pk_add_f32 v[72:73], v[72:73], 1.0 op_sel_hi:[1,0]
	v_pk_add_f32 v[74:75], v[74:75], 1.0 op_sel_hi:[1,0]
	v_pk_add_f32 v[76:77], v[76:77], 1.0 op_sel_hi:[1,0]
	v_pk_add_f32 v[78:79], v[78:79], 1.0 op_sel_hi:[1,0]
	v_pk_fma_f32 v[32:33], v[64:65], v[32:33], v[48:49]
	v_pk_fma_f32 v[34:35], v[66:67], v[34:35], v[50:51]
	v_pk_fma_f32 v[36:37], v[68:69], v[36:37], v[52:53]
	v_pk_fma_f32 v[38:39], v[70:71], v[38:39], v[54:55]
	v_pk_fma_f32 v[40:41], v[72:73], v[40:41], v[56:57]
	v_pk_fma_f32 v[42:43], v[74:75], v[42:43], v[58:59]
	v_pk_fma_f32 v[44:45], v[76:77], v[44:45], v[60:61]
	v_pk_fma_f32 v[46:47], v[78:79], v[46:47], v[62:63]
	v_cvt_pk_bf16_f32 v120, v32, v33
	v_cvt_pk_bf16_f32 v121, v34, v35
	v_cvt_pk_bf16_f32 v122, v36, v37
	v_cvt_pk_bf16_f32 v123, v38, v39
	v_cvt_pk_bf16_f32 v124, v40, v41
	v_cvt_pk_bf16_f32 v125, v42, v43
	v_cvt_pk_bf16_f32 v126, v44, v45
	v_cvt_pk_bf16_f32 v127, v46, v47
	global_store_dwordx2 v[132:133], v[120:121], off
	global_store_dwordx2 v[132:133], v[122:123], off offset:512
	global_store_dwordx2 v[132:133], v[124:125], off offset:1024
	global_store_dwordx2 v[132:133], v[126:127], off offset:1536
	v_lshl_add_u64 v[132:133], v[132:133], 0, v[152:153]
	global_load_dwordx4 v[32:35], v[128:129], off nt
	global_load_dwordx4 v[36:39], v[128:129], off offset:1024 nt
	global_load_dwordx4 v[40:43], v[128:129], off offset:2048 nt
	global_load_dwordx4 v[44:47], v[128:129], off offset:3072 nt
	v_lshl_add_u64 v[128:129], v[128:129], 0, v[150:151]
	s_cmp_lg_u32 s0, 2
	s_cbranch_scc1 .Lln0_nopark
	v_lshl_add_u64 v[128:129], s[60:61], 0, v[148:149]
.Lln0_nopark:
	v_add_f32_e32 v112, v0, v1
	v_add_f32_e32 v113, v2, v3
	v_add_f32_e32 v114, v4, v5
	v_add_f32_e32 v115, v6, v7
	v_add_f32_e32 v116, v8, v9
	v_add_f32_e32 v117, v10, v11
	v_add_f32_e32 v118, v12, v13
	v_add_f32_e32 v119, v14, v15
	v_add_f32_e32 v112, v112, v116
	v_add_f32_e32 v113, v113, v117
	v_add_f32_e32 v114, v114, v118
	v_add_f32_e32 v115, v115, v119
	v_add_f32_e32 v112, v112, v113
	v_add_f32_e32 v114, v114, v115
	v_add_f32_e32 v112, v112, v114
	s_nop 1
	v_add_f32_dpp v112, v112, v112 quad_perm:[1,0,3,2] row_mask:0xf bank_mask:0xf
	s_nop 1
	v_add_f32_dpp v112, v112, v112 quad_perm:[2,3,0,1] row_mask:0xf bank_mask:0xf
	s_nop 1
	v_add_f32_dpp v112, v112, v112 row_half_mirror row_mask:0xf bank_mask:0xf
	s_nop 1
	v_add_f32_dpp v112, v112, v112 row_mirror row_mask:0xf bank_mask:0xf
	s_nop 1
	v_add_f32_dpp v112, v112, v112 row_bcast:15 row_mask:0xa bank_mask:0xf
	s_nop 1
	v_add_f32_dpp v112, v112, v112 row_bcast:31 row_mask:0xc bank_mask:0xf
	s_nop 1
	v_readlane_b32 s2, v112, 63
	s_nop 1
	v_fmac_f32_e32 v0, s2, v142
	v_fmac_f32_e32 v1, s2, v142
	v_fmac_f32_e32 v2, s2, v142
	v_fmac_f32_e32 v3, s2, v142
	v_fmac_f32_e32 v4, s2, v142
	v_fmac_f32_e32 v5, s2, v142
	v_fmac_f32_e32 v6, s2, v142
	v_fmac_f32_e32 v7, s2, v142
	v_fmac_f32_e32 v8, s2, v142
	v_fmac_f32_e32 v9, s2, v142
	v_fmac_f32_e32 v10, s2, v142
	v_fmac_f32_e32 v11, s2, v142
	v_fmac_f32_e32 v12, s2, v142
	v_fmac_f32_e32 v13, s2, v142
	v_fmac_f32_e32 v14, s2, v142
	v_fmac_f32_e32 v15, s2, v142
	v_mul_f32_e32 v112, v0, v0
	v_mul_f32_e32 v113, v1, v1
	v_mul_f32_e32 v114, v2, v2
	v_mul_f32_e32 v115, v3, v3
	v_fmac_f32_e32 v112, v4, v4
	v_fmac_f32_e32 v113, v5, v5
	v_fmac_f32_e32 v114, v6, v6
	v_fmac_f32_e32 v115, v7, v7
	v_fmac_f32_e32 v112, v8, v8
	v_fmac_f32_e32 v113, v9, v9
	v_fmac_f32_e32 v114, v10, v10
	v_fmac_f32_e32 v115, v11, v11
	v_fmac_f32_e32 v112, v12, v12
	v_fmac_f32_e32 v113, v13, v13
	v_fmac_f32_e32 v114, v14, v14
	v_fmac_f32_e32 v115, v15, v15
	v_add_f32_e32 v112, v112, v113
	v_add_f32_e32 v114, v114, v115
	v_add_f32_e32 v112, v112, v114
	s_nop 1
	v_add_f32_dpp v112, v112, v112 quad_perm:[1,0,3,2] row_mask:0xf bank_mask:0xf
	s_nop 1
	v_add_f32_dpp v112, v112, v112 quad_perm:[2,3,0,1] row_mask:0xf bank_mask:0xf
	s_nop 1
	v_add_f32_dpp v112, v112, v112 row_half_mirror row_mask:0xf bank_mask:0xf
	s_nop 1
	v_add_f32_dpp v112, v112, v112 row_mirror row_mask:0xf bank_mask:0xf
	s_nop 1
	v_add_f32_dpp v112, v112, v112 row_bcast:15 row_mask:0xa bank_mask:0xf
	s_nop 1
	v_add_f32_dpp v112, v112, v112 row_bcast:31 row_mask:0xc bank_mask:0xf
	s_nop 1
	v_readlane_b32 s2, v112, 63
	s_nop 1
	v_mov_b32_e32 v113, 0x358637bd
	v_mov_b32_e32 v114, 0x3a800000
	v_fmac_f32_e32 v113, s2, v114
	v_rsq_f32_e32 v115, v113
	v_mul_f32_e32 v113, 0.5, v113
	v_mul_f32_e32 v116, v115, v115
	v_mov_b32_e32 v117, 0x3fc00000
	v_fma_f32 v116, -v113, v116, v117
	v_mul_f32_e32 v144, v115, v116
	v_pk_mul_f32 v[0:1], v[0:1], v[144:145] op_sel_hi:[1,0]
	v_pk_mul_f32 v[2:3], v[2:3], v[144:145] op_sel_hi:[1,0]
	v_pk_mul_f32 v[4:5], v[4:5], v[144:145] op_sel_hi:[1,0]
	v_pk_mul_f32 v[6:7], v[6:7], v[144:145] op_sel_hi:[1,0]
	v_pk_mul_f32 v[8:9], v[8:9], v[144:145] op_sel_hi:[1,0]
	v_pk_mul_f32 v[10:11], v[10:11], v[144:145] op_sel_hi:[1,0]
	v_pk_mul_f32 v[12:13], v[12:13], v[144:145] op_sel_hi:[1,0]
	v_pk_mul_f32 v[14:15], v[14:15], v[144:145] op_sel_hi:[1,0]
	v_pk_fma_f32 v[0:1], v[64:65], v[0:1], v[48:49]
	v_pk_fma_f32 v[2:3], v[66:67], v[2:3], v[50:51]
	v_pk_fma_f32 v[4:5], v[68:69], v[4:5], v[52:53]
	v_pk_fma_f32 v[6:7], v[70:71], v[6:7], v[54:55]
	v_pk_fma_f32 v[8:9], v[72:73], v[8:9], v[56:57]
	v_pk_fma_f32 v[10:11], v[74:75], v[10:11], v[58:59]
	v_pk_fma_f32 v[12:13], v[76:77], v[12:13], v[60:61]
	v_pk_fma_f32 v[14:15], v[78:79], v[14:15], v[62:63]
	v_cvt_pk_bf16_f32 v120, v0, v1
	v_cvt_pk_bf16_f32 v121, v2, v3
	v_cvt_pk_bf16_f32 v122, v4, v5
	v_cvt_pk_bf16_f32 v123, v6, v7
	v_cvt_pk_bf16_f32 v124, v8, v9
	v_cvt_pk_bf16_f32 v125, v10, v11
	v_cvt_pk_bf16_f32 v126, v12, v13
	v_cvt_pk_bf16_f32 v127, v14, v15
	global_store_dwordx2 v[132:133], v[120:121], off
	global_store_dwordx2 v[132:133], v[122:123], off offset:512
	global_store_dwordx2 v[132:133], v[124:125], off offset:1024
	global_store_dwordx2 v[132:133], v[126:127], off offset:1536
	v_lshl_add_u64 v[132:133], v[132:133], 0, v[152:153]
	global_load_dwordx4 v[48:51], v[134:135], off offset:-4096
	global_load_dwordx4 v[52:55], v[134:135], off offset:-3072
	global_load_dwordx4 v[56:59], v[134:135], off offset:-2048
	global_load_dwordx4 v[60:63], v[134:135], off offset:-1024
	global_load_dwordx4 v[64:67], v[134:135], off
	global_load_dwordx4 v[68:71], v[134:135], off offset:1024
	global_load_dwordx4 v[72:75], v[134:135], off offset:2048
	global_load_dwordx4 v[76:79], v[134:135], off offset:3072
	v_lshl_add_u64 v[134:135], v[134:135], 0, v[154:155]
	global_load_dwordx4 v[0:3], v[128:129], off nt
	global_load_dwordx4 v[4:7], v[128:129], off offset:1024 nt
	global_load_dwordx4 v[8:11], v[128:129], off offset:2048 nt
	global_load_dwordx4 v[12:15], v[128:129], off offset:3072 nt
	v_lshl_add_u64 v[128:129], v[128:129], 0, v[150:151]
	s_waitcnt vmcnt(24)
	v_add_f32_e32 v112, v16, v17
	v_add_f32_e32 v113, v18, v19
	v_add_f32_e32 v114, v20, v21
	v_add_f32_e32 v115, v22, v23
	v_add_f32_e32 v116, v24, v25
	v_add_f32_e32 v117, v26, v27
	v_add_f32_e32 v118, v28, v29
	v_add_f32_e32 v119, v30, v31
	v_add_f32_e32 v112, v112, v116
	v_add_f32_e32 v113, v113, v117
	v_add_f32_e32 v114, v114, v118
	v_add_f32_e32 v115, v115, v119
	v_add_f32_e32 v112, v112, v113
	v_add_f32_e32 v114, v114, v115
	v_add_f32_e32 v112, v112, v114
	s_nop 1
	v_add_f32_dpp v112, v112, v112 quad_perm:[1,0,3,2] row_mask:0xf bank_mask:0xf
	s_nop 1
	v_add_f32_dpp v112, v112, v112 quad_perm:[2,3,0,1] row_mask:0xf bank_mask:0xf
	s_nop 1
	v_add_f32_dpp v112, v112, v112 row_half_mirror row_mask:0xf bank_mask:0xf
	s_nop 1
	v_add_f32_dpp v112, v112, v112 row_mirror row_mask:0xf bank_mask:0xf
	s_nop 1
	v_add_f32_dpp v112, v112, v112 row_bcast:15 row_mask:0xa bank_mask:0xf
	s_nop 1
	v_add_f32_dpp v112, v112, v112 row_bcast:31 row_mask:0xc bank_mask:0xf
	s_nop 1
	v_readlane_b32 s2, v112, 63
	s_nop 1
	v_fmac_f32_e32 v16, s2, v142
	v_fmac_f32_e32 v17, s2, v142
	v_fmac_f32_e32 v18, s2, v142
	v_fmac_f32_e32 v19, s2, v142
	v_fmac_f32_e32 v20, s2, v142
	v_fmac_f32_e32 v21, s2, v142
	v_fmac_f32_e32 v22, s2, v142
	v_fmac_f32_e32 v23, s2, v142
	v_fmac_f32_e32 v24, s2, v142
	v_fmac_f32_e32 v25, s2, v142
	v_fmac_f32_e32 v26, s2, v142
	v_fmac_f32_e32 v27, s2, v142
	v_fmac_f32_e32 v28, s2, v142
	v_fmac_f32_e32 v29, s2, v142
	v_fmac_f32_e32 v30, s2, v142
	v_fmac_f32_e32 v31, s2, v142
	v_mul_f32_e32 v112, v16, v16
	v_mul_f32_e32 v113, v17, v17
	v_mul_f32_e32 v114, v18, v18
	v_mul_f32_e32 v115, v19, v19
	v_fmac_f32_e32 v112, v20, v20
	v_fmac_f32_e32 v113, v21, v21
	v_fmac_f32_e32 v114, v22, v22
	v_fmac_f32_e32 v115, v23, v23
	v_fmac_f32_e32 v112, v24, v24
	v_fmac_f32_e32 v113, v25, v25
	v_fmac_f32_e32 v114, v26, v26
	v_fmac_f32_e32 v115, v27, v27
	v_fmac_f32_e32 v112, v28, v28
	v_fmac_f32_e32 v113, v29, v29
	v_fmac_f32_e32 v114, v30, v30
	v_fmac_f32_e32 v115, v31, v31
	v_add_f32_e32 v112, v112, v113
	v_add_f32_e32 v114, v114, v115
	v_add_f32_e32 v112, v112, v114
	s_nop 1
	v_add_f32_dpp v112, v112, v112 quad_perm:[1,0,3,2] row_mask:0xf bank_mask:0xf
	s_nop 1
	v_add_f32_dpp v112, v112, v112 quad_perm:[2,3,0,1] row_mask:0xf bank_mask:0xf
	s_nop 1
	v_add_f32_dpp v112, v112, v112 row_half_mirror row_mask:0xf bank_mask:0xf
	s_nop 1
	v_add_f32_dpp v112, v112, v112 row_mirror row_mask:0xf bank_mask:0xf
	s_nop 1
	v_add_f32_dpp v112, v112, v112 row_bcast:15 row_mask:0xa bank_mask:0xf
	s_nop 1
	v_add_f32_dpp v112, v112, v112 row_bcast:31 row_mask:0xc bank_mask:0xf
	s_nop 1
	v_readlane_b32 s2, v112, 63
	s_nop 1
	v_mov_b32_e32 v113, 0x358637bd
	v_mov_b32_e32 v114, 0x3a800000
	v_fmac_f32_e32 v113, s2, v114
	v_rsq_f32_e32 v115, v113
	v_mul_f32_e32 v113, 0.5, v113
	v_mul_f32_e32 v116, v115, v115
	v_mov_b32_e32 v117, 0x3fc00000
	v_fma_f32 v116, -v113, v116, v117
	v_mul_f32_e32 v144, v115, v116
	v_pk_mul_f32 v[16:17], v[16:17], v[144:145] op_sel_hi:[1,0]
	v_pk_mul_f32 v[18:19], v[18:19], v[144:145] op_sel_hi:[1,0]
	v_pk_mul_f32 v[20:21], v[20:21], v[144:145] op_sel_hi:[1,0]
	v_pk_mul_f32 v[22:23], v[22:23], v[144:145] op_sel_hi:[1,0]
	v_pk_mul_f32 v[24:25], v[24:25], v[144:145] op_sel_hi:[1,0]
	v_pk_mul_f32 v[26:27], v[26:27], v[144:145] op_sel_hi:[1,0]
	v_pk_mul_f32 v[28:29], v[28:29], v[144:145] op_sel_hi:[1,0]
	v_pk_mul_f32 v[30:31], v[30:31], v[144:145] op_sel_hi:[1,0]
	s_waitcnt vmcnt(4)
	v_pk_add_f32 v[64:65], v[64:65], 1.0 op_sel_hi:[1,0]
	v_pk_add_f32 v[66:67], v[66:67], 1.0 op_sel_hi:[1,0]
	v_pk_add_f32 v[68:69], v[68:69], 1.0 op_sel_hi:[1,0]
	v_pk_add_f32 v[70:71], v[70:71], 1.0 op_sel_hi:[1,0]
	v_pk_add_f32 v[72:73], v[72:73], 1.0 op_sel_hi:[1,0]
	v_pk_add_f32 v[74:75], v[74:75], 1.0 op_sel_hi:[1,0]
	v_pk_add_f32 v[76:77], v[76:77], 1.0 op_sel_hi:[1,0]
	v_pk_add_f32 v[78:79], v[78:79], 1.0 op_sel_hi:[1,0]
	v_pk_fma_f32 v[16:17], v[64:65], v[16:17], v[48:49]
	v_pk_fma_f32 v[18:19], v[66:67], v[18:19], v[50:51]
	v_pk_fma_f32 v[20:21], v[68:69], v[20:21], v[52:53]
	v_pk_fma_f32 v[22:23], v[70:71], v[22:23], v[54:55]
	v_pk_fma_f32 v[24:25], v[72:73], v[24:25], v[56:57]
	v_pk_fma_f32 v[26:27], v[74:75], v[26:27], v[58:59]
	v_pk_fma_f32 v[28:29], v[76:77], v[28:29], v[60:61]
	v_pk_fma_f32 v[30:31], v[78:79], v[30:31], v[62:63]
	v_cvt_pk_bf16_f32 v120, v16, v17
	v_cvt_pk_bf16_f32 v121, v18, v19
	v_cvt_pk_bf16_f32 v122, v20, v21
	v_cvt_pk_bf16_f32 v123, v22, v23
	v_cvt_pk_bf16_f32 v124, v24, v25
	v_cvt_pk_bf16_f32 v125, v26, v27
	v_cvt_pk_bf16_f32 v126, v28, v29
	v_cvt_pk_bf16_f32 v127, v30, v31
	global_store_dwordx2 v[132:133], v[120:121], off
	global_store_dwordx2 v[132:133], v[122:123], off offset:512
	global_store_dwordx2 v[132:133], v[124:125], off offset:1024
	global_store_dwordx2 v[132:133], v[126:127], off offset:1536
	v_lshl_add_u64 v[132:133], v[132:133], 0, v[152:153]
	global_load_dwordx4 v[16:19], v[128:129], off nt
	global_load_dwordx4 v[20:23], v[128:129], off offset:1024 nt
	global_load_dwordx4 v[24:27], v[128:129], off offset:2048 nt
	global_load_dwordx4 v[28:31], v[128:129], off offset:3072 nt
	v_lshl_add_u64 v[128:129], v[128:129], 0, v[150:151]
	v_add_f32_e32 v112, v32, v33
	v_add_f32_e32 v113, v34, v35
	v_add_f32_e32 v114, v36, v37
	v_add_f32_e32 v115, v38, v39
	v_add_f32_e32 v116, v40, v41
	v_add_f32_e32 v117, v42, v43
	v_add_f32_e32 v118, v44, v45
	v_add_f32_e32 v119, v46, v47
	v_add_f32_e32 v112, v112, v116
	v_add_f32_e32 v113, v113, v117
	v_add_f32_e32 v114, v114, v118
	v_add_f32_e32 v115, v115, v119
	v_add_f32_e32 v112, v112, v113
	v_add_f32_e32 v114, v114, v115
	v_add_f32_e32 v112, v112, v114
	s_nop 1
	v_add_f32_dpp v112, v112, v112 quad_perm:[1,0,3,2] row_mask:0xf bank_mask:0xf
	s_nop 1
	v_add_f32_dpp v112, v112, v112 quad_perm:[2,3,0,1] row_mask:0xf bank_mask:0xf
	s_nop 1
	v_add_f32_dpp v112, v112, v112 row_half_mirror row_mask:0xf bank_mask:0xf
	s_nop 1
	v_add_f32_dpp v112, v112, v112 row_mirror row_mask:0xf bank_mask:0xf
	s_nop 1
	v_add_f32_dpp v112, v112, v112 row_bcast:15 row_mask:0xa bank_mask:0xf
	s_nop 1
	v_add_f32_dpp v112, v112, v112 row_bcast:31 row_mask:0xc bank_mask:0xf
	s_nop 1
	v_readlane_b32 s2, v112, 63
	s_nop 1
	v_fmac_f32_e32 v32, s2, v142
	v_fmac_f32_e32 v33, s2, v142
	v_fmac_f32_e32 v34, s2, v142
	v_fmac_f32_e32 v35, s2, v142
	v_fmac_f32_e32 v36, s2, v142
	v_fmac_f32_e32 v37, s2, v142
	v_fmac_f32_e32 v38, s2, v142
	v_fmac_f32_e32 v39, s2, v142
	v_fmac_f32_e32 v40, s2, v142
	v_fmac_f32_e32 v41, s2, v142
	v_fmac_f32_e32 v42, s2, v142
	v_fmac_f32_e32 v43, s2, v142
	v_fmac_f32_e32 v44, s2, v142
	v_fmac_f32_e32 v45, s2, v142
	v_fmac_f32_e32 v46, s2, v142
	v_fmac_f32_e32 v47, s2, v142
	v_mul_f32_e32 v112, v32, v32
	v_mul_f32_e32 v113, v33, v33
	v_mul_f32_e32 v114, v34, v34
	v_mul_f32_e32 v115, v35, v35
	v_fmac_f32_e32 v112, v36, v36
	v_fmac_f32_e32 v113, v37, v37
	v_fmac_f32_e32 v114, v38, v38
	v_fmac_f32_e32 v115, v39, v39
	v_fmac_f32_e32 v112, v40, v40
	v_fmac_f32_e32 v113, v41, v41
	v_fmac_f32_e32 v114, v42, v42
	v_fmac_f32_e32 v115, v43, v43
	v_fmac_f32_e32 v112, v44, v44
	v_fmac_f32_e32 v113, v45, v45
	v_fmac_f32_e32 v114, v46, v46
	v_fmac_f32_e32 v115, v47, v47
	v_add_f32_e32 v112, v112, v113
	v_add_f32_e32 v114, v114, v115
	v_add_f32_e32 v112, v112, v114
	s_nop 1
	v_add_f32_dpp v112, v112, v112 quad_perm:[1,0,3,2] row_mask:0xf bank_mask:0xf
	s_nop 1
	v_add_f32_dpp v112, v112, v112 quad_perm:[2,3,0,1] row_mask:0xf bank_mask:0xf
	s_nop 1
	v_add_f32_dpp v112, v112, v112 row_half_mirror row_mask:0xf bank_mask:0xf
	s_nop 1
	v_add_f32_dpp v112, v112, v112 row_mirror row_mask:0xf bank_mask:0xf
	s_nop 1
	v_add_f32_dpp v112, v112, v112 row_bcast:15 row_mask:0xa bank_mask:0xf
	s_nop 1
	v_add_f32_dpp v112, v112, v112 row_bcast:31 row_mask:0xc bank_mask:0xf
	s_nop 1
	v_readlane_b32 s2, v112, 63
	s_nop 1
	v_mov_b32_e32 v113, 0x358637bd
	v_mov_b32_e32 v114, 0x3a800000
	v_fmac_f32_e32 v113, s2, v114
	v_rsq_f32_e32 v115, v113
	v_mul_f32_e32 v113, 0.5, v113
	v_mul_f32_e32 v116, v115, v115
	v_mov_b32_e32 v117, 0x3fc00000
	v_fma_f32 v116, -v113, v116, v117
	v_mul_f32_e32 v144, v115, v116
	v_pk_mul_f32 v[32:33], v[32:33], v[144:145] op_sel_hi:[1,0]
	v_pk_mul_f32 v[34:35], v[34:35], v[144:145] op_sel_hi:[1,0]
	v_pk_mul_f32 v[36:37], v[36:37], v[144:145] op_sel_hi:[1,0]
	v_pk_mul_f32 v[38:39], v[38:39], v[144:145] op_sel_hi:[1,0]
	v_pk_mul_f32 v[40:41], v[40:41], v[144:145] op_sel_hi:[1,0]
	v_pk_mul_f32 v[42:43], v[42:43], v[144:145] op_sel_hi:[1,0]
	v_pk_mul_f32 v[44:45], v[44:45], v[144:145] op_sel_hi:[1,0]
	v_pk_mul_f32 v[46:47], v[46:47], v[144:145] op_sel_hi:[1,0]
	v_pk_fma_f32 v[32:33], v[64:65], v[32:33], v[48:49]
	v_pk_fma_f32 v[34:35], v[66:67], v[34:35], v[50:51]
	v_pk_fma_f32 v[36:37], v[68:69], v[36:37], v[52:53]
	v_pk_fma_f32 v[38:39], v[70:71], v[38:39], v[54:55]
	v_pk_fma_f32 v[40:41], v[72:73], v[40:41], v[56:57]
	v_pk_fma_f32 v[42:43], v[74:75], v[42:43], v[58:59]
	v_pk_fma_f32 v[44:45], v[76:77], v[44:45], v[60:61]
	v_pk_fma_f32 v[46:47], v[78:79], v[46:47], v[62:63]
	v_cvt_pk_bf16_f32 v120, v32, v33
	v_cvt_pk_bf16_f32 v121, v34, v35
	v_cvt_pk_bf16_f32 v122, v36, v37
	v_cvt_pk_bf16_f32 v123, v38, v39
	v_cvt_pk_bf16_f32 v124, v40, v41
	v_cvt_pk_bf16_f32 v125, v42, v43
	v_cvt_pk_bf16_f32 v126, v44, v45
	v_cvt_pk_bf16_f32 v127, v46, v47
	global_store_dwordx2 v[132:133], v[120:121], off
	global_store_dwordx2 v[132:133], v[122:123], off offset:512
	global_store_dwordx2 v[132:133], v[124:125], off offset:1024
	global_store_dwordx2 v[132:133], v[126:127], off offset:1536
	v_lshl_add_u64 v[132:133], v[132:133], 0, v[152:153]
	s_add_i32 s0, s0, 1
	s_cmp_lt_i32 s0, 3
	s_cbranch_scc1 .Lln0_loop
.LBB0_84:
	s_mov_b64 s[0:1], 0
.LBB0_85:
	s_mov_b64 s[18:19], 0

.LBB0_430:
	s_nop 0
	v_readlane_b32 s4, v255, 11
	v_readlane_b32 s5, v255, 12
	s_andn2_b64 vcc, exec, s[4:5]
	s_cbranch_vccnz .LBB0_439
	v_readlane_b32 s40, v255, 6
	s_nop 1
	s_cmp_lg_u32 s40, 0
	s_cbranch_scc1 .Lln1_layer1
	v_readlane_b32 s2, v254, 38
	v_lshrrev_b32_e32 v146, 6, v221
	v_and_b32_e32 v112, 63, v221
	v_mov_b32_e32 v150, 0x800000
	v_mov_b32_e32 v151, 0
	v_mov_b32_e32 v152, 0x400000
	v_mov_b32_e32 v153, 0
	v_mov_b32_e32 v154, 0x3000
	v_mov_b32_e32 v155, 0
	v_add_u32_e32 v146, s2, v146
	v_lshlrev_b32_e32 v148, 4, v112
	v_mov_b32_e32 v149, 0
	v_lshl_add_u32 v140, v146, 12, v148
	v_mov_b32_e32 v141, 0
	v_mov_b32_e32 v142, 0xba800000
	s_mov_b32 s0, 0
	v_add_u32_e32 v114, 0x1c000, v148
	v_mov_b32_e32 v115, 0
	v_lshl_add_u64 v[134:135], s[60:61], 0, v[114:115]
	v_lshlrev_b32_e32 v114, 3, v112
	v_lshl_add_u32 v114, v146, 11, v114
	s_add_u32 s42, s60, 0x3100000
	s_addc_u32 s43, s61, 0
	v_lshl_add_u64 v[132:133], s[42:43], 0, v[114:115]
	v_lshl_add_u64 v[128:129], s[98:99], 0, v[140:141]
	v_mov_b32_e32 v130, v128
	v_mov_b32_e32 v131, v129
	v_readlane_b32 s42, v255, 6
	s_lshl_b32 s42, s42, 12
	s_add_u32 s44, s94, s42
	s_addc_u32 s45, s95, 0
	s_add_u32 s42, s96, s42
	s_addc_u32 s43, s97, 0
	v_lshl_add_u64 v[136:137], s[44:45], 0, v[148:149]
	v_lshl_add_u64 v[138:139], s[42:43], 0, v[148:149]
	global_load_dwordx4 v[80:83], v[136:137], off
	global_load_dwordx4 v[84:87], v[136:137], off offset:1024
	global_load_dwordx4 v[88:91], v[136:137], off offset:2048
	global_load_dwordx4 v[92:95], v[136:137], off offset:3072
	global_load_dwordx4 v[96:99], v[138:139], off
	global_load_dwordx4 v[100:103], v[138:139], off offset:1024
	global_load_dwordx4 v[104:107], v[138:139], off offset:2048
	global_load_dwordx4 v[108:111], v[138:139], off offset:3072
	global_load_dwordx4 v[0:3], v[128:129], off nt
	global_load_dwordx4 v[4:7], v[128:129], off offset:1024 nt
	global_load_dwordx4 v[8:11], v[128:129], off offset:2048 nt
	global_load_dwordx4 v[12:15], v[128:129], off offset:3072 nt
	v_lshl_add_u64 v[128:129], v[128:129], 0, v[150:151]
	global_load_dword v156, v[134:135], off
	global_load_dword v156, v[134:135], off
	global_load_dword v156, v[134:135], off
	global_load_dword v156, v[134:135], off
	global_load_dword v156, v[134:135], off
	global_load_dword v156, v[134:135], off
	global_load_dword v156, v[134:135], off
	global_load_dword v156, v[134:135], off
	global_load_dwordx4 v[16:19], v[128:129], off nt
	global_load_dwordx4 v[20:23], v[128:129], off offset:1024 nt
	global_load_dwordx4 v[24:27], v[128:129], off offset:2048 nt
	global_load_dwordx4 v[28:31], v[128:129], off offset:3072 nt
	v_lshl_add_u64 v[128:129], v[128:129], 0, v[150:151]
	global_load_dword v156, v[134:135], off
	global_load_dword v156, v[134:135], off
	global_load_dword v156, v[134:135], off
	global_load_dword v156, v[134:135], off
	global_load_dword v156, v[134:135], off
	global_load_dword v156, v[134:135], off
	global_load_dword v156, v[134:135], off
	global_load_dword v156, v[134:135], off
.Lln1a_loop:
	global_load_dwordx4 v[48:51], v[134:135], off offset:-4096
	global_load_dwordx4 v[52:55], v[134:135], off offset:-3072
	global_load_dwordx4 v[56:59], v[134:135], off offset:-2048
	global_load_dwordx4 v[60:63], v[134:135], off offset:-1024
	global_load_dwordx4 v[64:67], v[134:135], off
	global_load_dwordx4 v[68:71], v[134:135], off offset:1024
	global_load_dwordx4 v[72:75], v[134:135], off offset:2048
	global_load_dwordx4 v[76:79], v[134:135], off offset:3072
	v_lshl_add_u64 v[134:135], v[134:135], 0, v[154:155]
	global_load_dwordx4 v[32:35], v[128:129], off nt
	global_load_dwordx4 v[36:39], v[128:129], off offset:1024 nt
	global_load_dwordx4 v[40:43], v[128:129], off offset:2048 nt
	global_load_dwordx4 v[44:47], v[128:129], off offset:3072 nt
	v_lshl_add_u64 v[128:129], v[128:129], 0, v[150:151]
	s_waitcnt vmcnt(32)
	v_add_f32_e32 v112, v0, v1
	v_add_f32_e32 v113, v2, v3
	v_add_f32_e32 v114, v4, v5
	v_add_f32_e32 v115, v6, v7
	v_add_f32_e32 v116, v8, v9
	v_add_f32_e32 v117, v10, v11
	v_add_f32_e32 v118, v12, v13
	v_add_f32_e32 v119, v14, v15
	v_add_f32_e32 v112, v112, v116
	v_add_f32_e32 v113, v113, v117
	v_add_f32_e32 v114, v114, v118
	v_add_f32_e32 v115, v115, v119
	v_add_f32_e32 v112, v112, v113
	v_add_f32_e32 v114, v114, v115
	v_add_f32_e32 v112, v112, v114
	s_nop 1
	v_add_f32_dpp v112, v112, v112 quad_perm:[1,0,3,2] row_mask:0xf bank_mask:0xf
	s_nop 1
	v_add_f32_dpp v112, v112, v112 quad_perm:[2,3,0,1] row_mask:0xf bank_mask:0xf
	s_nop 1
	v_add_f32_dpp v112, v112, v112 row_half_mirror row_mask:0xf bank_mask:0xf
	s_nop 1
	v_add_f32_dpp v112, v112, v112 row_mirror row_mask:0xf bank_mask:0xf
	s_nop 1
	v_add_f32_dpp v112, v112, v112 row_bcast:15 row_mask:0xa bank_mask:0xf
	s_nop 1
	v_add_f32_dpp v112, v112, v112 row_bcast:31 row_mask:0xc bank_mask:0xf
	s_nop 1
	v_readlane_b32 s2, v112, 63
	s_nop 1
	v_fmac_f32_e32 v0, s2, v142
	v_fmac_f32_e32 v1, s2, v142
	v_fmac_f32_e32 v2, s2, v142
	v_fmac_f32_e32 v3, s2, v142
	v_fmac_f32_e32 v4, s2, v142
	v_fmac_f32_e32 v5, s2, v142
	v_fmac_f32_e32 v6, s2, v142
	v_fmac_f32_e32 v7, s2, v142
	v_fmac_f32_e32 v8, s2, v142
	v_fmac_f32_e32 v9, s2, v142
	v_fmac_f32_e32 v10, s2, v142
	v_fmac_f32_e32 v11, s2, v142
	v_fmac_f32_e32 v12, s2, v142
	v_fmac_f32_e32 v13, s2, v142
	v_fmac_f32_e32 v14, s2, v142
	v_fmac_f32_e32 v15, s2, v142
	v_mul_f32_e32 v112, v0, v0
	v_mul_f32_e32 v113, v1, v1
	v_mul_f32_e32 v114, v2, v2
	v_mul_f32_e32 v115, v3, v3
	v_fmac_f32_e32 v112, v4, v4
	v_fmac_f32_e32 v113, v5, v5
	v_fmac_f32_e32 v114, v6, v6
	v_fmac_f32_e32 v115, v7, v7
	v_fmac_f32_e32 v112, v8, v8
	v_fmac_f32_e32 v113, v9, v9
	v_fmac_f32_e32 v114, v10, v10
	v_fmac_f32_e32 v115, v11, v11
	v_fmac_f32_e32 v112, v12, v12
	v_fmac_f32_e32 v113, v13, v13
	v_fmac_f32_e32 v114, v14, v14
	v_fmac_f32_e32 v115, v15, v15
	v_add_f32_e32 v112, v112, v113
	v_add_f32_e32 v114, v114, v115
	v_add_f32_e32 v112, v112, v114
	s_nop 1
	v_add_f32_dpp v112, v112, v112 quad_perm:[1,0,3,2] row_mask:0xf bank_mask:0xf
	s_nop 1
	v_add_f32_dpp v112, v112, v112 quad_perm:[2,3,0,1] row_mask:0xf bank_mask:0xf
	s_nop 1
	v_add_f32_dpp v112, v112, v112 row_half_mirror row_mask:0xf bank_mask:0xf
	s_nop 1
	v_add_f32_dpp v112, v112, v112 row_mirror row_mask:0xf bank_mask:0xf
	s_nop 1
	v_add_f32_dpp v112, v112, v112 row_bcast:15 row_mask:0xa bank_mask:0xf
	s_nop 1
	v_add_f32_dpp v112, v112, v112 row_bcast:31 row_mask:0xc bank_mask:0xf
	s_nop 1
	v_readlane_b32 s2, v112, 63
	s_nop 1
	v_mov_b32_e32 v113, 0x358637bd
	v_mov_b32_e32 v114, 0x3a800000
	v_fmac_f32_e32 v113, s2, v114
	v_rsq_f32_e32 v115, v113
	v_mul_f32_e32 v113, 0.5, v113
	v_mul_f32_e32 v116, v115, v115
	v_mov_b32_e32 v117, 0x3fc00000
	v_fma_f32 v116, -v113, v116, v117
	v_mul_f32_e32 v144, v115, v116
	v_pk_mul_f32 v[0:1], v[0:1], v[144:145] op_sel_hi:[1,0]
	v_pk_mul_f32 v[2:3], v[2:3], v[144:145] op_sel_hi:[1,0]
	v_pk_mul_f32 v[4:5], v[4:5], v[144:145] op_sel_hi:[1,0]
	v_pk_mul_f32 v[6:7], v[6:7], v[144:145] op_sel_hi:[1,0]
	v_pk_mul_f32 v[8:9], v[8:9], v[144:145] op_sel_hi:[1,0]
	v_pk_mul_f32 v[10:11], v[10:11], v[144:145] op_sel_hi:[1,0]
	v_pk_mul_f32 v[12:13], v[12:13], v[144:145] op_sel_hi:[1,0]
	v_pk_mul_f32 v[14:15], v[14:15], v[144:145] op_sel_hi:[1,0]
	v_pk_fma_f32 v[0:1], v[80:81], v[0:1], v[96:97]
	v_pk_fma_f32 v[2:3], v[82:83], v[2:3], v[98:99]
	v_pk_fma_f32 v[4:5], v[84:85], v[4:5], v[100:101]
	v_pk_fma_f32 v[6:7], v[86:87], v[6:7], v[102:103]
	v_pk_fma_f32 v[8:9], v[88:89], v[8:9], v[104:105]
	v_pk_fma_f32 v[10:11], v[90:91], v[10:11], v[106:107]
	v_pk_fma_f32 v[12:13], v[92:93], v[12:13], v[108:109]
	v_pk_fma_f32 v[14:15], v[94:95], v[14:15], v[110:111]
	global_store_dwordx4 v[130:131], v[0:3], off
	global_store_dwordx4 v[130:131], v[4:7], off offset:1024
	global_store_dwordx4 v[130:131], v[8:11], off offset:2048
	global_store_dwordx4 v[130:131], v[12:15], off offset:3072
	v_lshl_add_u64 v[130:131], v[130:131], 0, v[150:151]
	v_add_f32_e32 v112, v0, v1
	v_add_f32_e32 v113, v2, v3
	v_add_f32_e32 v114, v4, v5
	v_add_f32_e32 v115, v6, v7
	v_add_f32_e32 v116, v8, v9
	v_add_f32_e32 v117, v10, v11
	v_add_f32_e32 v118, v12, v13
	v_add_f32_e32 v119, v14, v15
	v_add_f32_e32 v112, v112, v116
	v_add_f32_e32 v113, v113, v117
	v_add_f32_e32 v114, v114, v118
	v_add_f32_e32 v115, v115, v119
	v_add_f32_e32 v112, v112, v113
	v_add_f32_e32 v114, v114, v115
	v_add_f32_e32 v112, v112, v114
	s_nop 1
	v_add_f32_dpp v112, v112, v112 quad_perm:[1,0,3,2] row_mask:0xf bank_mask:0xf
	s_nop 1
	v_add_f32_dpp v112, v112, v112 quad_perm:[2,3,0,1] row_mask:0xf bank_mask:0xf
	s_nop 1
	v_add_f32_dpp v112, v112, v112 row_half_mirror row_mask:0xf bank_mask:0xf
	s_nop 1
	v_add_f32_dpp v112, v112, v112 row_mirror row_mask:0xf bank_mask:0xf
	s_nop 1
	v_add_f32_dpp v112, v112, v112 row_bcast:15 row_mask:0xa bank_mask:0xf
	s_nop 1
	v_add_f32_dpp v112, v112, v112 row_bcast:31 row_mask:0xc bank_mask:0xf
	s_nop 1
	v_readlane_b32 s2, v112, 63
	s_nop 1
	v_fmac_f32_e32 v0, s2, v142
	v_fmac_f32_e32 v1, s2, v142
	v_fmac_f32_e32 v2, s2, v142
	v_fmac_f32_e32 v3, s2, v142
	v_fmac_f32_e32 v4, s2, v142
	v_fmac_f32_e32 v5, s2, v142
	v_fmac_f32_e32 v6, s2, v142
	v_fmac_f32_e32 v7, s2, v142
	v_fmac_f32_e32 v8, s2, v142
	v_fmac_f32_e32 v9, s2, v142
	v_fmac_f32_e32 v10, s2, v142
	v_fmac_f32_e32 v11, s2, v142
	v_fmac_f32_e32 v12, s2, v142
	v_fmac_f32_e32 v13, s2, v142
	v_fmac_f32_e32 v14, s2, v142
	v_fmac_f32_e32 v15, s2, v142
	v_mul_f32_e32 v112, v0, v0
	v_mul_f32_e32 v113, v1, v1
	v_mul_f32_e32 v114, v2, v2
	v_mul_f32_e32 v115, v3, v3
	v_fmac_f32_e32 v112, v4, v4
	v_fmac_f32_e32 v113, v5, v5
	v_fmac_f32_e32 v114, v6, v6
	v_fmac_f32_e32 v115, v7, v7
	v_fmac_f32_e32 v112, v8, v8
	v_fmac_f32_e32 v113, v9, v9
	v_fmac_f32_e32 v114, v10, v10
	v_fmac_f32_e32 v115, v11, v11
	v_fmac_f32_e32 v112, v12, v12
	v_fmac_f32_e32 v113, v13, v13
	v_fmac_f32_e32 v114, v14, v14
	v_fmac_f32_e32 v115, v15, v15
	v_add_f32_e32 v112, v112, v113
	v_add_f32_e32 v114, v114, v115
	v_add_f32_e32 v112, v112, v114
	s_nop 1
	v_add_f32_dpp v112, v112, v112 quad_perm:[1,0,3,2] row_mask:0xf bank_mask:0xf
	s_nop 1
	v_add_f32_dpp v112, v112, v112 quad_perm:[2,3,0,1] row_mask:0xf bank_mask:0xf
	s_nop 1
	v_add_f32_dpp v112, v112, v112 row_half_mirror row_mask:0xf bank_mask:0xf
	s_nop 1
	v_add_f32_dpp v112, v112, v112 row_mirror row_mask:0xf bank_mask:0xf
	s_nop 1
	v_add_f32_dpp v112, v112, v112 row_bcast:15 row_mask:0xa bank_mask:0xf
	s_nop 1
	v_add_f32_dpp v112, v112, v112 row_bcast:31 row_mask:0xc bank_mask:0xf
	s_nop 1
	v_readlane_b32 s2, v112, 63
	s_nop 1
	v_mov_b32_e32 v113, 0x358637bd
	v_mov_b32_e32 v114, 0x3a800000
	v_fmac_f32_e32 v113, s2, v114
	v_rsq_f32_e32 v115, v113
	v_mul_f32_e32 v113, 0.5, v113
	v_mul_f32_e32 v116, v115, v115
	v_mov_b32_e32 v117, 0x3fc00000
	v_fma_f32 v116, -v113, v116, v117
	v_mul_f32_e32 v144, v115, v116
	v_pk_mul_f32 v[0:1], v[0:1], v[144:145] op_sel_hi:[1,0]
	v_pk_mul_f32 v[2:3], v[2:3], v[144:145] op_sel_hi:[1,0]
	v_pk_mul_f32 v[4:5], v[4:5], v[144:145] op_sel_hi:[1,0]
	v_pk_mul_f32 v[6:7], v[6:7], v[144:145] op_sel_hi:[1,0]
	v_pk_mul_f32 v[8:9], v[8:9], v[144:145] op_sel_hi:[1,0]
	v_pk_mul_f32 v[10:11], v[10:11], v[144:145] op_sel_hi:[1,0]
	v_pk_mul_f32 v[12:13], v[12:13], v[144:145] op_sel_hi:[1,0]
	v_pk_mul_f32 v[14:15], v[14:15], v[144:145] op_sel_hi:[1,0]
	s_waitcnt vmcnt(8)
	v_pk_add_f32 v[64:65], v[64:65], 1.0 op_sel_hi:[1,0]
	v_pk_add_f32 v[66:67], v[66:67], 1.0 op_sel_hi:[1,0]
	v_pk_add_f32 v[68:69], v[68:69], 1.0 op_sel_hi:[1,0]
	v_pk_add_f32 v[70:71], v[70:71], 1.0 op_sel_hi:[1,0]
	v_pk_add_f32 v[72:73], v[72:73], 1.0 op_sel_hi:[1,0]
	v_pk_add_f32 v[74:75], v[74:75], 1.0 op_sel_hi:[1,0]
	v_pk_add_f32 v[76:77], v[76:77], 1.0 op_sel_hi:[1,0]
	v_pk_add_f32 v[78:79], v[78:79], 1.0 op_sel_hi:[1,0]
	v_pk_fma_f32 v[0:1], v[64:65], v[0:1], v[48:49]
	v_pk_fma_f32 v[2:3], v[66:67], v[2:3], v[50:51]
	v_pk_fma_f32 v[4:5], v[68:69], v[4:5], v[52:53]
	v_pk_fma_f32 v[6:7], v[70:71], v[6:7], v[54:55]
	v_pk_fma_f32 v[8:9], v[72:73], v[8:9], v[56:57]
	v_pk_fma_f32 v[10:11], v[74:75], v[10:11], v[58:59]
	v_pk_fma_f32 v[12:13], v[76:77], v[12:13], v[60:61]
	v_pk_fma_f32 v[14:15], v[78:79], v[14:15], v[62:63]
	v_cvt_pk_bf16_f32 v120, v0, v1
	v_cvt_pk_bf16_f32 v121, v2, v3
	v_cvt_pk_bf16_f32 v122, v4, v5
	v_cvt_pk_bf16_f32 v123, v6, v7
	v_cvt_pk_bf16_f32 v124, v8, v9
	v_cvt_pk_bf16_f32 v125, v10, v11
	v_cvt_pk_bf16_f32 v126, v12, v13
	v_cvt_pk_bf16_f32 v127, v14, v15
	global_store_dwordx2 v[132:133], v[120:121], off
	global_store_dwordx2 v[132:133], v[122:123], off offset:512
	global_store_dwordx2 v[132:133], v[124:125], off offset:1024
	global_store_dwordx2 v[132:133], v[126:127], off offset:1536
	v_lshl_add_u64 v[132:133], v[132:133], 0, v[152:153]
	global_load_dwordx4 v[0:3], v[128:129], off nt
	global_load_dwordx4 v[4:7], v[128:129], off offset:1024 nt
	global_load_dwordx4 v[8:11], v[128:129], off offset:2048 nt
	global_load_dwordx4 v[12:15], v[128:129], off offset:3072 nt
	v_lshl_add_u64 v[128:129], v[128:129], 0, v[150:151]
	v_add_f32_e32 v112, v16, v17
	v_add_f32_e32 v113, v18, v19
	v_add_f32_e32 v114, v20, v21
	v_add_f32_e32 v115, v22, v23
	v_add_f32_e32 v116, v24, v25
	v_add_f32_e32 v117, v26, v27
	v_add_f32_e32 v118, v28, v29
	v_add_f32_e32 v119, v30, v31
	v_add_f32_e32 v112, v112, v116
	v_add_f32_e32 v113, v113, v117
	v_add_f32_e32 v114, v114, v118
	v_add_f32_e32 v115, v115, v119
	v_add_f32_e32 v112, v112, v113
	v_add_f32_e32 v114, v114, v115
	v_add_f32_e32 v112, v112, v114
	s_nop 1
	v_add_f32_dpp v112, v112, v112 quad_perm:[1,0,3,2] row_mask:0xf bank_mask:0xf
	s_nop 1
	v_add_f32_dpp v112, v112, v112 quad_perm:[2,3,0,1] row_mask:0xf bank_mask:0xf
	s_nop 1
	v_add_f32_dpp v112, v112, v112 row_half_mirror row_mask:0xf bank_mask:0xf
	s_nop 1
	v_add_f32_dpp v112, v112, v112 row_mirror row_mask:0xf bank_mask:0xf
	s_nop 1
	v_add_f32_dpp v112, v112, v112 row_bcast:15 row_mask:0xa bank_mask:0xf
	s_nop 1
	v_add_f32_dpp v112, v112, v112 row_bcast:31 row_mask:0xc bank_mask:0xf
	s_nop 1
	v_readlane_b32 s2, v112, 63
	s_nop 1
	v_fmac_f32_e32 v16, s2, v142
	v_fmac_f32_e32 v17, s2, v142
	v_fmac_f32_e32 v18, s2, v142
	v_fmac_f32_e32 v19, s2, v142
	v_fmac_f32_e32 v20, s2, v142
	v_fmac_f32_e32 v21, s2, v142
	v_fmac_f32_e32 v22, s2, v142
	v_fmac_f32_e32 v23, s2, v142
	v_fmac_f32_e32 v24, s2, v142
	v_fmac_f32_e32 v25, s2, v142
	v_fmac_f32_e32 v26, s2, v142
	v_fmac_f32_e32 v27, s2, v142
	v_fmac_f32_e32 v28, s2, v142
	v_fmac_f32_e32 v29, s2, v142
	v_fmac_f32_e32 v30, s2, v142
	v_fmac_f32_e32 v31, s2, v142
	v_mul_f32_e32 v112, v16, v16
	v_mul_f32_e32 v113, v17, v17
	v_mul_f32_e32 v114, v18, v18
	v_mul_f32_e32 v115, v19, v19
	v_fmac_f32_e32 v112, v20, v20
	v_fmac_f32_e32 v113, v21, v21
	v_fmac_f32_e32 v114, v22, v22
	v_fmac_f32_e32 v115, v23, v23
	v_fmac_f32_e32 v112, v24, v24
	v_fmac_f32_e32 v113, v25, v25
	v_fmac_f32_e32 v114, v26, v26
	v_fmac_f32_e32 v115, v27, v27
	v_fmac_f32_e32 v112, v28, v28
	v_fmac_f32_e32 v113, v29, v29
	v_fmac_f32_e32 v114, v30, v30
	v_fmac_f32_e32 v115, v31, v31
	v_add_f32_e32 v112, v112, v113
	v_add_f32_e32 v114, v114, v115
	v_add_f32_e32 v112, v112, v114
	s_nop 1
	v_add_f32_dpp v112, v112, v112 quad_perm:[1,0,3,2] row_mask:0xf bank_mask:0xf
	s_nop 1
	v_add_f32_dpp v112, v112, v112 quad_perm:[2,3,0,1] row_mask:0xf bank_mask:0xf
	s_nop 1
	v_add_f32_dpp v112, v112, v112 row_half_mirror row_mask:0xf bank_mask:0xf
	s_nop 1
	v_add_f32_dpp v112, v112, v112 row_mirror row_mask:0xf bank_mask:0xf
	s_nop 1
	v_add_f32_dpp v112, v112, v112 row_bcast:15 row_mask:0xa bank_mask:0xf
	s_nop 1
	v_add_f32_dpp v112, v112, v112 row_bcast:31 row_mask:0xc bank_mask:0xf
	s_nop 1
	v_readlane_b32 s2, v112, 63
	s_nop 1
	v_mov_b32_e32 v113, 0x358637bd
	v_mov_b32_e32 v114, 0x3a800000
	v_fmac_f32_e32 v113, s2, v114
	v_rsq_f32_e32 v115, v113
	v_mul_f32_e32 v113, 0.5, v113
	v_mul_f32_e32 v116, v115, v115
	v_mov_b32_e32 v117, 0x3fc00000
	v_fma_f32 v116, -v113, v116, v117
	v_mul_f32_e32 v144, v115, v116
	v_pk_mul_f32 v[16:17], v[16:17], v[144:145] op_sel_hi:[1,0]
	v_pk_mul_f32 v[18:19], v[18:19], v[144:145] op_sel_hi:[1,0]
	v_pk_mul_f32 v[20:21], v[20:21], v[144:145] op_sel_hi:[1,0]
	v_pk_mul_f32 v[22:23], v[22:23], v[144:145] op_sel_hi:[1,0]
	v_pk_mul_f32 v[24:25], v[24:25], v[144:145] op_sel_hi:[1,0]
	v_pk_mul_f32 v[26:27], v[26:27], v[144:145] op_sel_hi:[1,0]
	v_pk_mul_f32 v[28:29], v[28:29], v[144:145] op_sel_hi:[1,0]
	v_pk_mul_f32 v[30:31], v[30:31], v[144:145] op_sel_hi:[1,0]
	v_pk_fma_f32 v[16:17], v[80:81], v[16:17], v[96:97]
	v_pk_fma_f32 v[18:19], v[82:83], v[18:19], v[98:99]
	v_pk_fma_f32 v[20:21], v[84:85], v[20:21], v[100:101]
	v_pk_fma_f32 v[22:23], v[86:87], v[22:23], v[102:103]
	v_pk_fma_f32 v[24:25], v[88:89], v[24:25], v[104:105]
	v_pk_fma_f32 v[26:27], v[90:91], v[26:27], v[106:107]
	v_pk_fma_f32 v[28:29], v[92:93], v[28:29], v[108:109]
	v_pk_fma_f32 v[30:31], v[94:95], v[30:31], v[110:111]
	global_store_dwordx4 v[130:131], v[16:19], off
	global_store_dwordx4 v[130:131], v[20:23], off offset:1024
	global_store_dwordx4 v[130:131], v[24:27], off offset:2048
	global_store_dwordx4 v[130:131], v[28:31], off offset:3072
	v_lshl_add_u64 v[130:131], v[130:131], 0, v[150:151]
	v_add_f32_e32 v112, v16, v17
	v_add_f32_e32 v113, v18, v19
	v_add_f32_e32 v114, v20, v21
	v_add_f32_e32 v115, v22, v23
	v_add_f32_e32 v116, v24, v25
	v_add_f32_e32 v117, v26, v27
	v_add_f32_e32 v118, v28, v29
	v_add_f32_e32 v119, v30, v31
	v_add_f32_e32 v112, v112, v116
	v_add_f32_e32 v113, v113, v117
	v_add_f32_e32 v114, v114, v118
	v_add_f32_e32 v115, v115, v119
	v_add_f32_e32 v112, v112, v113
	v_add_f32_e32 v114, v114, v115
	v_add_f32_e32 v112, v112, v114
	s_nop 1
	v_add_f32_dpp v112, v112, v112 quad_perm:[1,0,3,2] row_mask:0xf bank_mask:0xf
	s_nop 1
	v_add_f32_dpp v112, v112, v112 quad_perm:[2,3,0,1] row_mask:0xf bank_mask:0xf
	s_nop 1
	v_add_f32_dpp v112, v112, v112 row_half_mirror row_mask:0xf bank_mask:0xf
	s_nop 1
	v_add_f32_dpp v112, v112, v112 row_mirror row_mask:0xf bank_mask:0xf
	s_nop 1
	v_add_f32_dpp v112, v112, v112 row_bcast:15 row_mask:0xa bank_mask:0xf
	s_nop 1
	v_add_f32_dpp v112, v112, v112 row_bcast:31 row_mask:0xc bank_mask:0xf
	s_nop 1
	v_readlane_b32 s2, v112, 63
	s_nop 1
	v_fmac_f32_e32 v16, s2, v142
	v_fmac_f32_e32 v17, s2, v142
	v_fmac_f32_e32 v18, s2, v142
	v_fmac_f32_e32 v19, s2, v142
	v_fmac_f32_e32 v20, s2, v142
	v_fmac_f32_e32 v21, s2, v142
	v_fmac_f32_e32 v22, s2, v142
	v_fmac_f32_e32 v23, s2, v142
	v_fmac_f32_e32 v24, s2, v142
	v_fmac_f32_e32 v25, s2, v142
	v_fmac_f32_e32 v26, s2, v142
	v_fmac_f32_e32 v27, s2, v142
	v_fmac_f32_e32 v28, s2, v142
	v_fmac_f32_e32 v29, s2, v142
	v_fmac_f32_e32 v30, s2, v142
	v_fmac_f32_e32 v31, s2, v142
	v_mul_f32_e32 v112, v16, v16
	v_mul_f32_e32 v113, v17, v17
	v_mul_f32_e32 v114, v18, v18
	v_mul_f32_e32 v115, v19, v19
	v_fmac_f32_e32 v112, v20, v20
	v_fmac_f32_e32 v113, v21, v21
	v_fmac_f32_e32 v114, v22, v22
	v_fmac_f32_e32 v115, v23, v23
	v_fmac_f32_e32 v112, v24, v24
	v_fmac_f32_e32 v113, v25, v25
	v_fmac_f32_e32 v114, v26, v26
	v_fmac_f32_e32 v115, v27, v27
	v_fmac_f32_e32 v112, v28, v28
	v_fmac_f32_e32 v113, v29, v29
	v_fmac_f32_e32 v114, v30, v30
	v_fmac_f32_e32 v115, v31, v31
	v_add_f32_e32 v112, v112, v113
	v_add_f32_e32 v114, v114, v115
	v_add_f32_e32 v112, v112, v114
	s_nop 1
	v_add_f32_dpp v112, v112, v112 quad_perm:[1,0,3,2] row_mask:0xf bank_mask:0xf
	s_nop 1
	v_add_f32_dpp v112, v112, v112 quad_perm:[2,3,0,1] row_mask:0xf bank_mask:0xf
	s_nop 1
	v_add_f32_dpp v112, v112, v112 row_half_mirror row_mask:0xf bank_mask:0xf
	s_nop 1
	v_add_f32_dpp v112, v112, v112 row_mirror row_mask:0xf bank_mask:0xf
	s_nop 1
	v_add_f32_dpp v112, v112, v112 row_bcast:15 row_mask:0xa bank_mask:0xf
	s_nop 1
	v_add_f32_dpp v112, v112, v112 row_bcast:31 row_mask:0xc bank_mask:0xf
	s_nop 1
	v_readlane_b32 s2, v112, 63
	s_nop 1
	v_mov_b32_e32 v113, 0x358637bd
	v_mov_b32_e32 v114, 0x3a800000
	v_fmac_f32_e32 v113, s2, v114
	v_rsq_f32_e32 v115, v113
	v_mul_f32_e32 v113, 0.5, v113
	v_mul_f32_e32 v116, v115, v115
	v_mov_b32_e32 v117, 0x3fc00000
	v_fma_f32 v116, -v113, v116, v117
	v_mul_f32_e32 v144, v115, v116
	v_pk_mul_f32 v[16:17], v[16:17], v[144:145] op_sel_hi:[1,0]
	v_pk_mul_f32 v[18:19], v[18:19], v[144:145] op_sel_hi:[1,0]
	v_pk_mul_f32 v[20:21], v[20:21], v[144:145] op_sel_hi:[1,0]
	v_pk_mul_f32 v[22:23], v[22:23], v[144:145] op_sel_hi:[1,0]
	v_pk_mul_f32 v[24:25], v[24:25], v[144:145] op_sel_hi:[1,0]
	v_pk_mul_f32 v[26:27], v[26:27], v[144:145] op_sel_hi:[1,0]
	v_pk_mul_f32 v[28:29], v[28:29], v[144:145] op_sel_hi:[1,0]
	v_pk_mul_f32 v[30:31], v[30:31], v[144:145] op_sel_hi:[1,0]
	v_pk_fma_f32 v[16:17], v[64:65], v[16:17], v[48:49]
	v_pk_fma_f32 v[18:19], v[66:67], v[18:19], v[50:51]
	v_pk_fma_f32 v[20:21], v[68:69], v[20:21], v[52:53]
	v_pk_fma_f32 v[22:23], v[70:71], v[22:23], v[54:55]
	v_pk_fma_f32 v[24:25], v[72:73], v[24:25], v[56:57]
	v_pk_fma_f32 v[26:27], v[74:75], v[26:27], v[58:59]
	v_pk_fma_f32 v[28:29], v[76:77], v[28:29], v[60:61]
	v_pk_fma_f32 v[30:31], v[78:79], v[30:31], v[62:63]
	v_cvt_pk_bf16_f32 v120, v16, v17
	v_cvt_pk_bf16_f32 v121, v18, v19
	v_cvt_pk_bf16_f32 v122, v20, v21
	v_cvt_pk_bf16_f32 v123, v22, v23
	v_cvt_pk_bf16_f32 v124, v24, v25
	v_cvt_pk_bf16_f32 v125, v26, v27
	v_cvt_pk_bf16_f32 v126, v28, v29
	v_cvt_pk_bf16_f32 v127, v30, v31
	global_store_dwordx2 v[132:133], v[120:121], off
	global_store_dwordx2 v[132:133], v[122:123], off offset:512
	global_store_dwordx2 v[132:133], v[124:125], off offset:1024
	global_store_dwordx2 v[132:133], v[126:127], off offset:1536
	v_lshl_add_u64 v[132:133], v[132:133], 0, v[152:153]
	global_load_dwordx4 v[48:51], v[134:135], off offset:-4096
	global_load_dwordx4 v[52:55], v[134:135], off offset:-3072
	global_load_dwordx4 v[56:59], v[134:135], off offset:-2048
	global_load_dwordx4 v[60:63], v[134:135], off offset:-1024
	global_load_dwordx4 v[64:67], v[134:135], off
	global_load_dwordx4 v[68:71], v[134:135], off offset:1024
	global_load_dwordx4 v[72:75], v[134:135], off offset:2048
	global_load_dwordx4 v[76:79], v[134:135], off offset:3072
	v_lshl_add_u64 v[134:135], v[134:135], 0, v[154:155]
	global_load_dwordx4 v[16:19], v[128:129], off nt
	global_load_dwordx4 v[20:23], v[128:129], off offset:1024 nt
	global_load_dwordx4 v[24:27], v[128:129], off offset:2048 nt
	global_load_dwordx4 v[28:31], v[128:129], off offset:3072 nt
	v_lshl_add_u64 v[128:129], v[128:129], 0, v[150:151]
	s_waitcnt vmcnt(32)
	v_add_f32_e32 v112, v32, v33
	v_add_f32_e32 v113, v34, v35
	v_add_f32_e32 v114, v36, v37
	v_add_f32_e32 v115, v38, v39
	v_add_f32_e32 v116, v40, v41
	v_add_f32_e32 v117, v42, v43
	v_add_f32_e32 v118, v44, v45
	v_add_f32_e32 v119, v46, v47
	v_add_f32_e32 v112, v112, v116
	v_add_f32_e32 v113, v113, v117
	v_add_f32_e32 v114, v114, v118
	v_add_f32_e32 v115, v115, v119
	v_add_f32_e32 v112, v112, v113
	v_add_f32_e32 v114, v114, v115
	v_add_f32_e32 v112, v112, v114
	s_nop 1
	v_add_f32_dpp v112, v112, v112 quad_perm:[1,0,3,2] row_mask:0xf bank_mask:0xf
	s_nop 1
	v_add_f32_dpp v112, v112, v112 quad_perm:[2,3,0,1] row_mask:0xf bank_mask:0xf
	s_nop 1
	v_add_f32_dpp v112, v112, v112 row_half_mirror row_mask:0xf bank_mask:0xf
	s_nop 1
	v_add_f32_dpp v112, v112, v112 row_mirror row_mask:0xf bank_mask:0xf
	s_nop 1
	v_add_f32_dpp v112, v112, v112 row_bcast:15 row_mask:0xa bank_mask:0xf
	s_nop 1
	v_add_f32_dpp v112, v112, v112 row_bcast:31 row_mask:0xc bank_mask:0xf
	s_nop 1
	v_readlane_b32 s2, v112, 63
	s_nop 1
	v_fmac_f32_e32 v32, s2, v142
	v_fmac_f32_e32 v33, s2, v142
	v_fmac_f32_e32 v34, s2, v142
	v_fmac_f32_e32 v35, s2, v142
	v_fmac_f32_e32 v36, s2, v142
	v_fmac_f32_e32 v37, s2, v142
	v_fmac_f32_e32 v38, s2, v142
	v_fmac_f32_e32 v39, s2, v142
	v_fmac_f32_e32 v40, s2, v142
	v_fmac_f32_e32 v41, s2, v142
	v_fmac_f32_e32 v42, s2, v142
	v_fmac_f32_e32 v43, s2, v142
	v_fmac_f32_e32 v44, s2, v142
	v_fmac_f32_e32 v45, s2, v142
	v_fmac_f32_e32 v46, s2, v142
	v_fmac_f32_e32 v47, s2, v142
	v_mul_f32_e32 v112, v32, v32
	v_mul_f32_e32 v113, v33, v33
	v_mul_f32_e32 v114, v34, v34
	v_mul_f32_e32 v115, v35, v35
	v_fmac_f32_e32 v112, v36, v36
	v_fmac_f32_e32 v113, v37, v37
	v_fmac_f32_e32 v114, v38, v38
	v_fmac_f32_e32 v115, v39, v39
	v_fmac_f32_e32 v112, v40, v40
	v_fmac_f32_e32 v113, v41, v41
	v_fmac_f32_e32 v114, v42, v42
	v_fmac_f32_e32 v115, v43, v43
	v_fmac_f32_e32 v112, v44, v44
	v_fmac_f32_e32 v113, v45, v45
	v_fmac_f32_e32 v114, v46, v46
	v_fmac_f32_e32 v115, v47, v47
	v_add_f32_e32 v112, v112, v113
	v_add_f32_e32 v114, v114, v115
	v_add_f32_e32 v112, v112, v114
	s_nop 1
	v_add_f32_dpp v112, v112, v112 quad_perm:[1,0,3,2] row_mask:0xf bank_mask:0xf
	s_nop 1
	v_add_f32_dpp v112, v112, v112 quad_perm:[2,3,0,1] row_mask:0xf bank_mask:0xf
	s_nop 1
	v_add_f32_dpp v112, v112, v112 row_half_mirror row_mask:0xf bank_mask:0xf
	s_nop 1
	v_add_f32_dpp v112, v112, v112 row_mirror row_mask:0xf bank_mask:0xf
	s_nop 1
	v_add_f32_dpp v112, v112, v112 row_bcast:15 row_mask:0xa bank_mask:0xf
	s_nop 1
	v_add_f32_dpp v112, v112, v112 row_bcast:31 row_mask:0xc bank_mask:0xf
	s_nop 1
	v_readlane_b32 s2, v112, 63
	s_nop 1
	v_mov_b32_e32 v113, 0x358637bd
	v_mov_b32_e32 v114, 0x3a800000
	v_fmac_f32_e32 v113, s2, v114
	v_rsq_f32_e32 v115, v113
	v_mul_f32_e32 v113, 0.5, v113
	v_mul_f32_e32 v116, v115, v115
	v_mov_b32_e32 v117, 0x3fc00000
	v_fma_f32 v116, -v113, v116, v117
	v_mul_f32_e32 v144, v115, v116
	v_pk_mul_f32 v[32:33], v[32:33], v[144:145] op_sel_hi:[1,0]
	v_pk_mul_f32 v[34:35], v[34:35], v[144:145] op_sel_hi:[1,0]
	v_pk_mul_f32 v[36:37], v[36:37], v[144:145] op_sel_hi:[1,0]
	v_pk_mul_f32 v[38:39], v[38:39], v[144:145] op_sel_hi:[1,0]
	v_pk_mul_f32 v[40:41], v[40:41], v[144:145] op_sel_hi:[1,0]
	v_pk_mul_f32 v[42:43], v[42:43], v[144:145] op_sel_hi:[1,0]
	v_pk_mul_f32 v[44:45], v[44:45], v[144:145] op_sel_hi:[1,0]
	v_pk_mul_f32 v[46:47], v[46:47], v[144:145] op_sel_hi:[1,0]
	v_pk_fma_f32 v[32:33], v[80:81], v[32:33], v[96:97]
	v_pk_fma_f32 v[34:35], v[82:83], v[34:35], v[98:99]
	v_pk_fma_f32 v[36:37], v[84:85], v[36:37], v[100:101]
	v_pk_fma_f32 v[38:39], v[86:87], v[38:39], v[102:103]
	v_pk_fma_f32 v[40:41], v[88:89], v[40:41], v[104:105]
	v_pk_fma_f32 v[42:43], v[90:91], v[42:43], v[106:107]
	v_pk_fma_f32 v[44:45], v[92:93], v[44:45], v[108:109]
	v_pk_fma_f32 v[46:47], v[94:95], v[46:47], v[110:111]
	global_store_dwordx4 v[130:131], v[32:35], off
	global_store_dwordx4 v[130:131], v[36:39], off offset:1024
	global_store_dwordx4 v[130:131], v[40:43], off offset:2048
	global_store_dwordx4 v[130:131], v[44:47], off offset:3072
	v_lshl_add_u64 v[130:131], v[130:131], 0, v[150:151]
	v_add_f32_e32 v112, v32, v33
	v_add_f32_e32 v113, v34, v35
	v_add_f32_e32 v114, v36, v37
	v_add_f32_e32 v115, v38, v39
	v_add_f32_e32 v116, v40, v41
	v_add_f32_e32 v117, v42, v43
	v_add_f32_e32 v118, v44, v45
	v_add_f32_e32 v119, v46, v47
	v_add_f32_e32 v112, v112, v116
	v_add_f32_e32 v113, v113, v117
	v_add_f32_e32 v114, v114, v118
	v_add_f32_e32 v115, v115, v119
	v_add_f32_e32 v112, v112, v113
	v_add_f32_e32 v114, v114, v115
	v_add_f32_e32 v112, v112, v114
	s_nop 1
	v_add_f32_dpp v112, v112, v112 quad_perm:[1,0,3,2] row_mask:0xf bank_mask:0xf
	s_nop 1
	v_add_f32_dpp v112, v112, v112 quad_perm:[2,3,0,1] row_mask:0xf bank_mask:0xf
	s_nop 1
	v_add_f32_dpp v112, v112, v112 row_half_mirror row_mask:0xf bank_mask:0xf
	s_nop 1
	v_add_f32_dpp v112, v112, v112 row_mirror row_mask:0xf bank_mask:0xf
	s_nop 1
	v_add_f32_dpp v112, v112, v112 row_bcast:15 row_mask:0xa bank_mask:0xf
	s_nop 1
	v_add_f32_dpp v112, v112, v112 row_bcast:31 row_mask:0xc bank_mask:0xf
	s_nop 1
	v_readlane_b32 s2, v112, 63
	s_nop 1
	v_fmac_f32_e32 v32, s2, v142
	v_fmac_f32_e32 v33, s2, v142
	v_fmac_f32_e32 v34, s2, v142
	v_fmac_f32_e32 v35, s2, v142
	v_fmac_f32_e32 v36, s2, v142
	v_fmac_f32_e32 v37, s2, v142
	v_fmac_f32_e32 v38, s2, v142
	v_fmac_f32_e32 v39, s2, v142
	v_fmac_f32_e32 v40, s2, v142
	v_fmac_f32_e32 v41, s2, v142
	v_fmac_f32_e32 v42, s2, v142
	v_fmac_f32_e32 v43, s2, v142
	v_fmac_f32_e32 v44, s2, v142
	v_fmac_f32_e32 v45, s2, v142
	v_fmac_f32_e32 v46, s2, v142
	v_fmac_f32_e32 v47, s2, v142
	v_mul_f32_e32 v112, v32, v32
	v_mul_f32_e32 v113, v33, v33
	v_mul_f32_e32 v114, v34, v34
	v_mul_f32_e32 v115, v35, v35
	v_fmac_f32_e32 v112, v36, v36
	v_fmac_f32_e32 v113, v37, v37
	v_fmac_f32_e32 v114, v38, v38
	v_fmac_f32_e32 v115, v39, v39
	v_fmac_f32_e32 v112, v40, v40
	v_fmac_f32_e32 v113, v41, v41
	v_fmac_f32_e32 v114, v42, v42
	v_fmac_f32_e32 v115, v43, v43
	v_fmac_f32_e32 v112, v44, v44
	v_fmac_f32_e32 v113, v45, v45
	v_fmac_f32_e32 v114, v46, v46
	v_fmac_f32_e32 v115, v47, v47
	v_add_f32_e32 v112, v112, v113
	v_add_f32_e32 v114, v114, v115
	v_add_f32_e32 v112, v112, v114
	s_nop 1
	v_add_f32_dpp v112, v112, v112 quad_perm:[1,0,3,2] row_mask:0xf bank_mask:0xf
	s_nop 1
	v_add_f32_dpp v112, v112, v112 quad_perm:[2,3,0,1] row_mask:0xf bank_mask:0xf
	s_nop 1
	v_add_f32_dpp v112, v112, v112 row_half_mirror row_mask:0xf bank_mask:0xf
	s_nop 1
	v_add_f32_dpp v112, v112, v112 row_mirror row_mask:0xf bank_mask:0xf
	s_nop 1
	v_add_f32_dpp v112, v112, v112 row_bcast:15 row_mask:0xa bank_mask:0xf
	s_nop 1
	v_add_f32_dpp v112, v112, v112 row_bcast:31 row_mask:0xc bank_mask:0xf
	s_nop 1
	v_readlane_b32 s2, v112, 63
	s_nop 1
	v_mov_b32_e32 v113, 0x358637bd
	v_mov_b32_e32 v114, 0x3a800000
	v_fmac_f32_e32 v113, s2, v114
	v_rsq_f32_e32 v115, v113
	v_mul_f32_e32 v113, 0.5, v113
	v_mul_f32_e32 v116, v115, v115
	v_mov_b32_e32 v117, 0x3fc00000
	v_fma_f32 v116, -v113, v116, v117
	v_mul_f32_e32 v144, v115, v116
	v_pk_mul_f32 v[32:33], v[32:33], v[144:145] op_sel_hi:[1,0]
	v_pk_mul_f32 v[34:35], v[34:35], v[144:145] op_sel_hi:[1,0]
	v_pk_mul_f32 v[36:37], v[36:37], v[144:145] op_sel_hi:[1,0]
	v_pk_mul_f32 v[38:39], v[38:39], v[144:145] op_sel_hi:[1,0]
	v_pk_mul_f32 v[40:41], v[40:41], v[144:145] op_sel_hi:[1,0]
	v_pk_mul_f32 v[42:43], v[42:43], v[144:145] op_sel_hi:[1,0]
	v_pk_mul_f32 v[44:45], v[44:45], v[144:145] op_sel_hi:[1,0]
	v_pk_mul_f32 v[46:47], v[46:47], v[144:145] op_sel_hi:[1,0]
	s_waitcnt vmcnt(8)
	v_pk_add_f32 v[64:65], v[64:65], 1.0 op_sel_hi:[1,0]
	v_pk_add_f32 v[66:67], v[66:67], 1.0 op_sel_hi:[1,0]
	v_pk_add_f32 v[68:69], v[68:69], 1.0 op_sel_hi:[1,0]
	v_pk_add_f32 v[70:71], v[70:71], 1.0 op_sel_hi:[1,0]
	v_pk_add_f32 v[72:73], v[72:73], 1.0 op_sel_hi:[1,0]
	v_pk_add_f32 v[74:75], v[74:75], 1.0 op_sel_hi:[1,0]
	v_pk_add_f32 v[76:77], v[76:77], 1.0 op_sel_hi:[1,0]
	v_pk_add_f32 v[78:79], v[78:79], 1.0 op_sel_hi:[1,0]
	v_pk_fma_f32 v[32:33], v[64:65], v[32:33], v[48:49]
	v_pk_fma_f32 v[34:35], v[66:67], v[34:35], v[50:51]
	v_pk_fma_f32 v[36:37], v[68:69], v[36:37], v[52:53]
	v_pk_fma_f32 v[38:39], v[70:71], v[38:39], v[54:55]
	v_pk_fma_f32 v[40:41], v[72:73], v[40:41], v[56:57]
	v_pk_fma_f32 v[42:43], v[74:75], v[42:43], v[58:59]
	v_pk_fma_f32 v[44:45], v[76:77], v[44:45], v[60:61]
	v_pk_fma_f32 v[46:47], v[78:79], v[46:47], v[62:63]
	v_cvt_pk_bf16_f32 v120, v32, v33
	v_cvt_pk_bf16_f32 v121, v34, v35
	v_cvt_pk_bf16_f32 v122, v36, v37
	v_cvt_pk_bf16_f32 v123, v38, v39
	v_cvt_pk_bf16_f32 v124, v40, v41
	v_cvt_pk_bf16_f32 v125, v42, v43
	v_cvt_pk_bf16_f32 v126, v44, v45
	v_cvt_pk_bf16_f32 v127, v46, v47
	global_store_dwordx2 v[132:133], v[120:121], off
	global_store_dwordx2 v[132:133], v[122:123], off offset:512
	global_store_dwordx2 v[132:133], v[124:125], off offset:1024
	global_store_dwordx2 v[132:133], v[126:127], off offset:1536
	v_lshl_add_u64 v[132:133], v[132:133], 0, v[152:153]
	global_load_dwordx4 v[32:35], v[128:129], off nt
	global_load_dwordx4 v[36:39], v[128:129], off offset:1024 nt
	global_load_dwordx4 v[40:43], v[128:129], off offset:2048 nt
	global_load_dwordx4 v[44:47], v[128:129], off offset:3072 nt
	v_lshl_add_u64 v[128:129], v[128:129], 0, v[150:151]
	s_cmp_lg_u32 s0, 2
	s_cbranch_scc1 .Lln1a_nopark
	v_lshl_add_u64 v[128:129], s[60:61], 0, v[148:149]
.Lln1a_nopark:
	v_add_f32_e32 v112, v0, v1
	v_add_f32_e32 v113, v2, v3
	v_add_f32_e32 v114, v4, v5
	v_add_f32_e32 v115, v6, v7
	v_add_f32_e32 v116, v8, v9
	v_add_f32_e32 v117, v10, v11
	v_add_f32_e32 v118, v12, v13
	v_add_f32_e32 v119, v14, v15
	v_add_f32_e32 v112, v112, v116
	v_add_f32_e32 v113, v113, v117
	v_add_f32_e32 v114, v114, v118
	v_add_f32_e32 v115, v115, v119
	v_add_f32_e32 v112, v112, v113
	v_add_f32_e32 v114, v114, v115
	v_add_f32_e32 v112, v112, v114
	s_nop 1
	v_add_f32_dpp v112, v112, v112 quad_perm:[1,0,3,2] row_mask:0xf bank_mask:0xf
	s_nop 1
	v_add_f32_dpp v112, v112, v112 quad_perm:[2,3,0,1] row_mask:0xf bank_mask:0xf
	s_nop 1
	v_add_f32_dpp v112, v112, v112 row_half_mirror row_mask:0xf bank_mask:0xf
	s_nop 1
	v_add_f32_dpp v112, v112, v112 row_mirror row_mask:0xf bank_mask:0xf
	s_nop 1
	v_add_f32_dpp v112, v112, v112 row_bcast:15 row_mask:0xa bank_mask:0xf
	s_nop 1
	v_add_f32_dpp v112, v112, v112 row_bcast:31 row_mask:0xc bank_mask:0xf
	s_nop 1
	v_readlane_b32 s2, v112, 63
	s_nop 1
	v_fmac_f32_e32 v0, s2, v142
	v_fmac_f32_e32 v1, s2, v142
	v_fmac_f32_e32 v2, s2, v142
	v_fmac_f32_e32 v3, s2, v142
	v_fmac_f32_e32 v4, s2, v142
	v_fmac_f32_e32 v5, s2, v142
	v_fmac_f32_e32 v6, s2, v142
	v_fmac_f32_e32 v7, s2, v142
	v_fmac_f32_e32 v8, s2, v142
	v_fmac_f32_e32 v9, s2, v142
	v_fmac_f32_e32 v10, s2, v142
	v_fmac_f32_e32 v11, s2, v142
	v_fmac_f32_e32 v12, s2, v142
	v_fmac_f32_e32 v13, s2, v142
	v_fmac_f32_e32 v14, s2, v142
	v_fmac_f32_e32 v15, s2, v142
	v_mul_f32_e32 v112, v0, v0
	v_mul_f32_e32 v113, v1, v1
	v_mul_f32_e32 v114, v2, v2
	v_mul_f32_e32 v115, v3, v3
	v_fmac_f32_e32 v112, v4, v4
	v_fmac_f32_e32 v113, v5, v5
	v_fmac_f32_e32 v114, v6, v6
	v_fmac_f32_e32 v115, v7, v7
	v_fmac_f32_e32 v112, v8, v8
	v_fmac_f32_e32 v113, v9, v9
	v_fmac_f32_e32 v114, v10, v10
	v_fmac_f32_e32 v115, v11, v11
	v_fmac_f32_e32 v112, v12, v12
	v_fmac_f32_e32 v113, v13, v13
	v_fmac_f32_e32 v114, v14, v14
	v_fmac_f32_e32 v115, v15, v15
	v_add_f32_e32 v112, v112, v113
	v_add_f32_e32 v114, v114, v115
	v_add_f32_e32 v112, v112, v114
	s_nop 1
	v_add_f32_dpp v112, v112, v112 quad_perm:[1,0,3,2] row_mask:0xf bank_mask:0xf
	s_nop 1
	v_add_f32_dpp v112, v112, v112 quad_perm:[2,3,0,1] row_mask:0xf bank_mask:0xf
	s_nop 1
	v_add_f32_dpp v112, v112, v112 row_half_mirror row_mask:0xf bank_mask:0xf
	s_nop 1
	v_add_f32_dpp v112, v112, v112 row_mirror row_mask:0xf bank_mask:0xf
	s_nop 1
	v_add_f32_dpp v112, v112, v112 row_bcast:15 row_mask:0xa bank_mask:0xf
	s_nop 1
	v_add_f32_dpp v112, v112, v112 row_bcast:31 row_mask:0xc bank_mask:0xf
	s_nop 1
	v_readlane_b32 s2, v112, 63
	s_nop 1
	v_mov_b32_e32 v113, 0x358637bd
	v_mov_b32_e32 v114, 0x3a800000
	v_fmac_f32_e32 v113, s2, v114
	v_rsq_f32_e32 v115, v113
	v_mul_f32_e32 v113, 0.5, v113
	v_mul_f32_e32 v116, v115, v115
	v_mov_b32_e32 v117, 0x3fc00000
	v_fma_f32 v116, -v113, v116, v117
	v_mul_f32_e32 v144, v115, v116
	v_pk_mul_f32 v[0:1], v[0:1], v[144:145] op_sel_hi:[1,0]
	v_pk_mul_f32 v[2:3], v[2:3], v[144:145] op_sel_hi:[1,0]
	v_pk_mul_f32 v[4:5], v[4:5], v[144:145] op_sel_hi:[1,0]
	v_pk_mul_f32 v[6:7], v[6:7], v[144:145] op_sel_hi:[1,0]
	v_pk_mul_f32 v[8:9], v[8:9], v[144:145] op_sel_hi:[1,0]
	v_pk_mul_f32 v[10:11], v[10:11], v[144:145] op_sel_hi:[1,0]
	v_pk_mul_f32 v[12:13], v[12:13], v[144:145] op_sel_hi:[1,0]
	v_pk_mul_f32 v[14:15], v[14:15], v[144:145] op_sel_hi:[1,0]
	v_pk_fma_f32 v[0:1], v[80:81], v[0:1], v[96:97]
	v_pk_fma_f32 v[2:3], v[82:83], v[2:3], v[98:99]
	v_pk_fma_f32 v[4:5], v[84:85], v[4:5], v[100:101]
	v_pk_fma_f32 v[6:7], v[86:87], v[6:7], v[102:103]
	v_pk_fma_f32 v[8:9], v[88:89], v[8:9], v[104:105]
	v_pk_fma_f32 v[10:11], v[90:91], v[10:11], v[106:107]
	v_pk_fma_f32 v[12:13], v[92:93], v[12:13], v[108:109]
	v_pk_fma_f32 v[14:15], v[94:95], v[14:15], v[110:111]
	global_store_dwordx4 v[130:131], v[0:3], off
	global_store_dwordx4 v[130:131], v[4:7], off offset:1024
	global_store_dwordx4 v[130:131], v[8:11], off offset:2048
	global_store_dwordx4 v[130:131], v[12:15], off offset:3072
	v_lshl_add_u64 v[130:131], v[130:131], 0, v[150:151]
	v_add_f32_e32 v112, v0, v1
	v_add_f32_e32 v113, v2, v3
	v_add_f32_e32 v114, v4, v5
	v_add_f32_e32 v115, v6, v7
	v_add_f32_e32 v116, v8, v9
	v_add_f32_e32 v117, v10, v11
	v_add_f32_e32 v118, v12, v13
	v_add_f32_e32 v119, v14, v15
	v_add_f32_e32 v112, v112, v116
	v_add_f32_e32 v113, v113, v117
	v_add_f32_e32 v114, v114, v118
	v_add_f32_e32 v115, v115, v119
	v_add_f32_e32 v112, v112, v113
	v_add_f32_e32 v114, v114, v115
	v_add_f32_e32 v112, v112, v114
	s_nop 1
	v_add_f32_dpp v112, v112, v112 quad_perm:[1,0,3,2] row_mask:0xf bank_mask:0xf
	s_nop 1
	v_add_f32_dpp v112, v112, v112 quad_perm:[2,3,0,1] row_mask:0xf bank_mask:0xf
	s_nop 1
	v_add_f32_dpp v112, v112, v112 row_half_mirror row_mask:0xf bank_mask:0xf
	s_nop 1
	v_add_f32_dpp v112, v112, v112 row_mirror row_mask:0xf bank_mask:0xf
	s_nop 1
	v_add_f32_dpp v112, v112, v112 row_bcast:15 row_mask:0xa bank_mask:0xf
	s_nop 1
	v_add_f32_dpp v112, v112, v112 row_bcast:31 row_mask:0xc bank_mask:0xf
	s_nop 1
	v_readlane_b32 s2, v112, 63
	s_nop 1
	v_fmac_f32_e32 v0, s2, v142
	v_fmac_f32_e32 v1, s2, v142
	v_fmac_f32_e32 v2, s2, v142
	v_fmac_f32_e32 v3, s2, v142
	v_fmac_f32_e32 v4, s2, v142
	v_fmac_f32_e32 v5, s2, v142
	v_fmac_f32_e32 v6, s2, v142
	v_fmac_f32_e32 v7, s2, v142
	v_fmac_f32_e32 v8, s2, v142
	v_fmac_f32_e32 v9, s2, v142
	v_fmac_f32_e32 v10, s2, v142
	v_fmac_f32_e32 v11, s2, v142
	v_fmac_f32_e32 v12, s2, v142
	v_fmac_f32_e32 v13, s2, v142
	v_fmac_f32_e32 v14, s2, v142
	v_fmac_f32_e32 v15, s2, v142
	v_mul_f32_e32 v112, v0, v0
	v_mul_f32_e32 v113, v1, v1
	v_mul_f32_e32 v114, v2, v2
	v_mul_f32_e32 v115, v3, v3
	v_fmac_f32_e32 v112, v4, v4
	v_fmac_f32_e32 v113, v5, v5
	v_fmac_f32_e32 v114, v6, v6
	v_fmac_f32_e32 v115, v7, v7
	v_fmac_f32_e32 v112, v8, v8
	v_fmac_f32_e32 v113, v9, v9
	v_fmac_f32_e32 v114, v10, v10
	v_fmac_f32_e32 v115, v11, v11
	v_fmac_f32_e32 v112, v12, v12
	v_fmac_f32_e32 v113, v13, v13
	v_fmac_f32_e32 v114, v14, v14
	v_fmac_f32_e32 v115, v15, v15
	v_add_f32_e32 v112, v112, v113
	v_add_f32_e32 v114, v114, v115
	v_add_f32_e32 v112, v112, v114
	s_nop 1
	v_add_f32_dpp v112, v112, v112 quad_perm:[1,0,3,2] row_mask:0xf bank_mask:0xf
	s_nop 1
	v_add_f32_dpp v112, v112, v112 quad_perm:[2,3,0,1] row_mask:0xf bank_mask:0xf
	s_nop 1
	v_add_f32_dpp v112, v112, v112 row_half_mirror row_mask:0xf bank_mask:0xf
	s_nop 1
	v_add_f32_dpp v112, v112, v112 row_mirror row_mask:0xf bank_mask:0xf
	s_nop 1
	v_add_f32_dpp v112, v112, v112 row_bcast:15 row_mask:0xa bank_mask:0xf
	s_nop 1
	v_add_f32_dpp v112, v112, v112 row_bcast:31 row_mask:0xc bank_mask:0xf
	s_nop 1
	v_readlane_b32 s2, v112, 63
	s_nop 1
	v_mov_b32_e32 v113, 0x358637bd
	v_mov_b32_e32 v114, 0x3a800000
	v_fmac_f32_e32 v113, s2, v114
	v_rsq_f32_e32 v115, v113
	v_mul_f32_e32 v113, 0.5, v113
	v_mul_f32_e32 v116, v115, v115
	v_mov_b32_e32 v117, 0x3fc00000
	v_fma_f32 v116, -v113, v116, v117
	v_mul_f32_e32 v144, v115, v116
	v_pk_mul_f32 v[0:1], v[0:1], v[144:145] op_sel_hi:[1,0]
	v_pk_mul_f32 v[2:3], v[2:3], v[144:145] op_sel_hi:[1,0]
	v_pk_mul_f32 v[4:5], v[4:5], v[144:145] op_sel_hi:[1,0]
	v_pk_mul_f32 v[6:7], v[6:7], v[144:145] op_sel_hi:[1,0]
	v_pk_mul_f32 v[8:9], v[8:9], v[144:145] op_sel_hi:[1,0]
	v_pk_mul_f32 v[10:11], v[10:11], v[144:145] op_sel_hi:[1,0]
	v_pk_mul_f32 v[12:13], v[12:13], v[144:145] op_sel_hi:[1,0]
	v_pk_mul_f32 v[14:15], v[14:15], v[144:145] op_sel_hi:[1,0]
	v_pk_fma_f32 v[0:1], v[64:65], v[0:1], v[48:49]
	v_pk_fma_f32 v[2:3], v[66:67], v[2:3], v[50:51]
	v_pk_fma_f32 v[4:5], v[68:69], v[4:5], v[52:53]
	v_pk_fma_f32 v[6:7], v[70:71], v[6:7], v[54:55]
	v_pk_fma_f32 v[8:9], v[72:73], v[8:9], v[56:57]
	v_pk_fma_f32 v[10:11], v[74:75], v[10:11], v[58:59]
	v_pk_fma_f32 v[12:13], v[76:77], v[12:13], v[60:61]
	v_pk_fma_f32 v[14:15], v[78:79], v[14:15], v[62:63]
	v_cvt_pk_bf16_f32 v120, v0, v1
	v_cvt_pk_bf16_f32 v121, v2, v3
	v_cvt_pk_bf16_f32 v122, v4, v5
	v_cvt_pk_bf16_f32 v123, v6, v7
	v_cvt_pk_bf16_f32 v124, v8, v9
	v_cvt_pk_bf16_f32 v125, v10, v11
	v_cvt_pk_bf16_f32 v126, v12, v13
	v_cvt_pk_bf16_f32 v127, v14, v15
	global_store_dwordx2 v[132:133], v[120:121], off
	global_store_dwordx2 v[132:133], v[122:123], off offset:512
	global_store_dwordx2 v[132:133], v[124:125], off offset:1024
	global_store_dwordx2 v[132:133], v[126:127], off offset:1536
	v_lshl_add_u64 v[132:133], v[132:133], 0, v[152:153]
	global_load_dwordx4 v[48:51], v[134:135], off offset:-4096
	global_load_dwordx4 v[52:55], v[134:135], off offset:-3072
	global_load_dwordx4 v[56:59], v[134:135], off offset:-2048
	global_load_dwordx4 v[60:63], v[134:135], off offset:-1024
	global_load_dwordx4 v[64:67], v[134:135], off
	global_load_dwordx4 v[68:71], v[134:135], off offset:1024
	global_load_dwordx4 v[72:75], v[134:135], off offset:2048
	global_load_dwordx4 v[76:79], v[134:135], off offset:3072
	v_lshl_add_u64 v[134:135], v[134:135], 0, v[154:155]
	global_load_dwordx4 v[0:3], v[128:129], off nt
	global_load_dwordx4 v[4:7], v[128:129], off offset:1024 nt
	global_load_dwordx4 v[8:11], v[128:129], off offset:2048 nt
	global_load_dwordx4 v[12:15], v[128:129], off offset:3072 nt
	v_lshl_add_u64 v[128:129], v[128:129], 0, v[150:151]
	s_waitcnt vmcnt(32)
	v_add_f32_e32 v112, v16, v17
	v_add_f32_e32 v113, v18, v19
	v_add_f32_e32 v114, v20, v21
	v_add_f32_e32 v115, v22, v23
	v_add_f32_e32 v116, v24, v25
	v_add_f32_e32 v117, v26, v27
	v_add_f32_e32 v118, v28, v29
	v_add_f32_e32 v119, v30, v31
	v_add_f32_e32 v112, v112, v116
	v_add_f32_e32 v113, v113, v117
	v_add_f32_e32 v114, v114, v118
	v_add_f32_e32 v115, v115, v119
	v_add_f32_e32 v112, v112, v113
	v_add_f32_e32 v114, v114, v115
	v_add_f32_e32 v112, v112, v114
	s_nop 1
	v_add_f32_dpp v112, v112, v112 quad_perm:[1,0,3,2] row_mask:0xf bank_mask:0xf
	s_nop 1
	v_add_f32_dpp v112, v112, v112 quad_perm:[2,3,0,1] row_mask:0xf bank_mask:0xf
	s_nop 1
	v_add_f32_dpp v112, v112, v112 row_half_mirror row_mask:0xf bank_mask:0xf
	s_nop 1
	v_add_f32_dpp v112, v112, v112 row_mirror row_mask:0xf bank_mask:0xf
	s_nop 1
	v_add_f32_dpp v112, v112, v112 row_bcast:15 row_mask:0xa bank_mask:0xf
	s_nop 1
	v_add_f32_dpp v112, v112, v112 row_bcast:31 row_mask:0xc bank_mask:0xf
	s_nop 1
	v_readlane_b32 s2, v112, 63
	s_nop 1
	v_fmac_f32_e32 v16, s2, v142
	v_fmac_f32_e32 v17, s2, v142
	v_fmac_f32_e32 v18, s2, v142
	v_fmac_f32_e32 v19, s2, v142
	v_fmac_f32_e32 v20, s2, v142
	v_fmac_f32_e32 v21, s2, v142
	v_fmac_f32_e32 v22, s2, v142
	v_fmac_f32_e32 v23, s2, v142
	v_fmac_f32_e32 v24, s2, v142
	v_fmac_f32_e32 v25, s2, v142
	v_fmac_f32_e32 v26, s2, v142
	v_fmac_f32_e32 v27, s2, v142
	v_fmac_f32_e32 v28, s2, v142
	v_fmac_f32_e32 v29, s2, v142
	v_fmac_f32_e32 v30, s2, v142
	v_fmac_f32_e32 v31, s2, v142
	v_mul_f32_e32 v112, v16, v16
	v_mul_f32_e32 v113, v17, v17
	v_mul_f32_e32 v114, v18, v18
	v_mul_f32_e32 v115, v19, v19
	v_fmac_f32_e32 v112, v20, v20
	v_fmac_f32_e32 v113, v21, v21
	v_fmac_f32_e32 v114, v22, v22
	v_fmac_f32_e32 v115, v23, v23
	v_fmac_f32_e32 v112, v24, v24
	v_fmac_f32_e32 v113, v25, v25
	v_fmac_f32_e32 v114, v26, v26
	v_fmac_f32_e32 v115, v27, v27
	v_fmac_f32_e32 v112, v28, v28
	v_fmac_f32_e32 v113, v29, v29
	v_fmac_f32_e32 v114, v30, v30
	v_fmac_f32_e32 v115, v31, v31
	v_add_f32_e32 v112, v112, v113
	v_add_f32_e32 v114, v114, v115
	v_add_f32_e32 v112, v112, v114
	s_nop 1
	v_add_f32_dpp v112, v112, v112 quad_perm:[1,0,3,2] row_mask:0xf bank_mask:0xf
	s_nop 1
	v_add_f32_dpp v112, v112, v112 quad_perm:[2,3,0,1] row_mask:0xf bank_mask:0xf
	s_nop 1
	v_add_f32_dpp v112, v112, v112 row_half_mirror row_mask:0xf bank_mask:0xf
	s_nop 1
	v_add_f32_dpp v112, v112, v112 row_mirror row_mask:0xf bank_mask:0xf
	s_nop 1
	v_add_f32_dpp v112, v112, v112 row_bcast:15 row_mask:0xa bank_mask:0xf
	s_nop 1
	v_add_f32_dpp v112, v112, v112 row_bcast:31 row_mask:0xc bank_mask:0xf
	s_nop 1
	v_readlane_b32 s2, v112, 63
	s_nop 1
	v_mov_b32_e32 v113, 0x358637bd
	v_mov_b32_e32 v114, 0x3a800000
	v_fmac_f32_e32 v113, s2, v114
	v_rsq_f32_e32 v115, v113
	v_mul_f32_e32 v113, 0.5, v113
	v_mul_f32_e32 v116, v115, v115
	v_mov_b32_e32 v117, 0x3fc00000
	v_fma_f32 v116, -v113, v116, v117
	v_mul_f32_e32 v144, v115, v116
	v_pk_mul_f32 v[16:17], v[16:17], v[144:145] op_sel_hi:[1,0]
	v_pk_mul_f32 v[18:19], v[18:19], v[144:145] op_sel_hi:[1,0]
	v_pk_mul_f32 v[20:21], v[20:21], v[144:145] op_sel_hi:[1,0]
	v_pk_mul_f32 v[22:23], v[22:23], v[144:145] op_sel_hi:[1,0]
	v_pk_mul_f32 v[24:25], v[24:25], v[144:145] op_sel_hi:[1,0]
	v_pk_mul_f32 v[26:27], v[26:27], v[144:145] op_sel_hi:[1,0]
	v_pk_mul_f32 v[28:29], v[28:29], v[144:145] op_sel_hi:[1,0]
	v_pk_mul_f32 v[30:31], v[30:31], v[144:145] op_sel_hi:[1,0]
	v_pk_fma_f32 v[16:17], v[80:81], v[16:17], v[96:97]
	v_pk_fma_f32 v[18:19], v[82:83], v[18:19], v[98:99]
	v_pk_fma_f32 v[20:21], v[84:85], v[20:21], v[100:101]
	v_pk_fma_f32 v[22:23], v[86:87], v[22:23], v[102:103]
	v_pk_fma_f32 v[24:25], v[88:89], v[24:25], v[104:105]
	v_pk_fma_f32 v[26:27], v[90:91], v[26:27], v[106:107]
	v_pk_fma_f32 v[28:29], v[92:93], v[28:29], v[108:109]
	v_pk_fma_f32 v[30:31], v[94:95], v[30:31], v[110:111]
	global_store_dwordx4 v[130:131], v[16:19], off
	global_store_dwordx4 v[130:131], v[20:23], off offset:1024
	global_store_dwordx4 v[130:131], v[24:27], off offset:2048
	global_store_dwordx4 v[130:131], v[28:31], off offset:3072
	v_lshl_add_u64 v[130:131], v[130:131], 0, v[150:151]
	v_add_f32_e32 v112, v16, v17
	v_add_f32_e32 v113, v18, v19
	v_add_f32_e32 v114, v20, v21
	v_add_f32_e32 v115, v22, v23
	v_add_f32_e32 v116, v24, v25
	v_add_f32_e32 v117, v26, v27
	v_add_f32_e32 v118, v28, v29
	v_add_f32_e32 v119, v30, v31
	v_add_f32_e32 v112, v112, v116
	v_add_f32_e32 v113, v113, v117
	v_add_f32_e32 v114, v114, v118
	v_add_f32_e32 v115, v115, v119
	v_add_f32_e32 v112, v112, v113
	v_add_f32_e32 v114, v114, v115
	v_add_f32_e32 v112, v112, v114
	s_nop 1
	v_add_f32_dpp v112, v112, v112 quad_perm:[1,0,3,2] row_mask:0xf bank_mask:0xf
	s_nop 1
	v_add_f32_dpp v112, v112, v112 quad_perm:[2,3,0,1] row_mask:0xf bank_mask:0xf
	s_nop 1
	v_add_f32_dpp v112, v112, v112 row_half_mirror row_mask:0xf bank_mask:0xf
	s_nop 1
	v_add_f32_dpp v112, v112, v112 row_mirror row_mask:0xf bank_mask:0xf
	s_nop 1
	v_add_f32_dpp v112, v112, v112 row_bcast:15 row_mask:0xa bank_mask:0xf
	s_nop 1
	v_add_f32_dpp v112, v112, v112 row_bcast:31 row_mask:0xc bank_mask:0xf
	s_nop 1
	v_readlane_b32 s2, v112, 63
	s_nop 1
	v_fmac_f32_e32 v16, s2, v142
	v_fmac_f32_e32 v17, s2, v142
	v_fmac_f32_e32 v18, s2, v142
	v_fmac_f32_e32 v19, s2, v142
	v_fmac_f32_e32 v20, s2, v142
	v_fmac_f32_e32 v21, s2, v142
	v_fmac_f32_e32 v22, s2, v142
	v_fmac_f32_e32 v23, s2, v142
	v_fmac_f32_e32 v24, s2, v142
	v_fmac_f32_e32 v25, s2, v142
	v_fmac_f32_e32 v26, s2, v142
	v_fmac_f32_e32 v27, s2, v142
	v_fmac_f32_e32 v28, s2, v142
	v_fmac_f32_e32 v29, s2, v142
	v_fmac_f32_e32 v30, s2, v142
	v_fmac_f32_e32 v31, s2, v142
	v_mul_f32_e32 v112, v16, v16
	v_mul_f32_e32 v113, v17, v17
	v_mul_f32_e32 v114, v18, v18
	v_mul_f32_e32 v115, v19, v19
	v_fmac_f32_e32 v112, v20, v20
	v_fmac_f32_e32 v113, v21, v21
	v_fmac_f32_e32 v114, v22, v22
	v_fmac_f32_e32 v115, v23, v23
	v_fmac_f32_e32 v112, v24, v24
	v_fmac_f32_e32 v113, v25, v25
	v_fmac_f32_e32 v114, v26, v26
	v_fmac_f32_e32 v115, v27, v27
	v_fmac_f32_e32 v112, v28, v28
	v_fmac_f32_e32 v113, v29, v29
	v_fmac_f32_e32 v114, v30, v30
	v_fmac_f32_e32 v115, v31, v31
	v_add_f32_e32 v112, v112, v113
	v_add_f32_e32 v114, v114, v115
	v_add_f32_e32 v112, v112, v114
	s_nop 1
	v_add_f32_dpp v112, v112, v112 quad_perm:[1,0,3,2] row_mask:0xf bank_mask:0xf
	s_nop 1
	v_add_f32_dpp v112, v112, v112 quad_perm:[2,3,0,1] row_mask:0xf bank_mask:0xf
	s_nop 1
	v_add_f32_dpp v112, v112, v112 row_half_mirror row_mask:0xf bank_mask:0xf
	s_nop 1
	v_add_f32_dpp v112, v112, v112 row_mirror row_mask:0xf bank_mask:0xf
	s_nop 1
	v_add_f32_dpp v112, v112, v112 row_bcast:15 row_mask:0xa bank_mask:0xf
	s_nop 1
	v_add_f32_dpp v112, v112, v112 row_bcast:31 row_mask:0xc bank_mask:0xf
	s_nop 1
	v_readlane_b32 s2, v112, 63
	s_nop 1
	v_mov_b32_e32 v113, 0x358637bd
	v_mov_b32_e32 v114, 0x3a800000
	v_fmac_f32_e32 v113, s2, v114
	v_rsq_f32_e32 v115, v113
	v_mul_f32_e32 v113, 0.5, v113
	v_mul_f32_e32 v116, v115, v115
	v_mov_b32_e32 v117, 0x3fc00000
	v_fma_f32 v116, -v113, v116, v117
	v_mul_f32_e32 v144, v115, v116
	v_pk_mul_f32 v[16:17], v[16:17], v[144:145] op_sel_hi:[1,0]
	v_pk_mul_f32 v[18:19], v[18:19], v[144:145] op_sel_hi:[1,0]
	v_pk_mul_f32 v[20:21], v[20:21], v[144:145] op_sel_hi:[1,0]
	v_pk_mul_f32 v[22:23], v[22:23], v[144:145] op_sel_hi:[1,0]
	v_pk_mul_f32 v[24:25], v[24:25], v[144:145] op_sel_hi:[1,0]
	v_pk_mul_f32 v[26:27], v[26:27], v[144:145] op_sel_hi:[1,0]
	v_pk_mul_f32 v[28:29], v[28:29], v[144:145] op_sel_hi:[1,0]
	v_pk_mul_f32 v[30:31], v[30:31], v[144:145] op_sel_hi:[1,0]
	s_waitcnt vmcnt(8)
	v_pk_add_f32 v[64:65], v[64:65], 1.0 op_sel_hi:[1,0]
	v_pk_add_f32 v[66:67], v[66:67], 1.0 op_sel_hi:[1,0]
	v_pk_add_f32 v[68:69], v[68:69], 1.0 op_sel_hi:[1,0]
	v_pk_add_f32 v[70:71], v[70:71], 1.0 op_sel_hi:[1,0]
	v_pk_add_f32 v[72:73], v[72:73], 1.0 op_sel_hi:[1,0]
	v_pk_add_f32 v[74:75], v[74:75], 1.0 op_sel_hi:[1,0]
	v_pk_add_f32 v[76:77], v[76:77], 1.0 op_sel_hi:[1,0]
	v_pk_add_f32 v[78:79], v[78:79], 1.0 op_sel_hi:[1,0]
	v_pk_fma_f32 v[16:17], v[64:65], v[16:17], v[48:49]
	v_pk_fma_f32 v[18:19], v[66:67], v[18:19], v[50:51]
	v_pk_fma_f32 v[20:21], v[68:69], v[20:21], v[52:53]
	v_pk_fma_f32 v[22:23], v[70:71], v[22:23], v[54:55]
	v_pk_fma_f32 v[24:25], v[72:73], v[24:25], v[56:57]
	v_pk_fma_f32 v[26:27], v[74:75], v[26:27], v[58:59]
	v_pk_fma_f32 v[28:29], v[76:77], v[28:29], v[60:61]
	v_pk_fma_f32 v[30:31], v[78:79], v[30:31], v[62:63]
	v_cvt_pk_bf16_f32 v120, v16, v17
	v_cvt_pk_bf16_f32 v121, v18, v19
	v_cvt_pk_bf16_f32 v122, v20, v21
	v_cvt_pk_bf16_f32 v123, v22, v23
	v_cvt_pk_bf16_f32 v124, v24, v25
	v_cvt_pk_bf16_f32 v125, v26, v27
	v_cvt_pk_bf16_f32 v126, v28, v29
	v_cvt_pk_bf16_f32 v127, v30, v31
	global_store_dwordx2 v[132:133], v[120:121], off
	global_store_dwordx2 v[132:133], v[122:123], off offset:512
	global_store_dwordx2 v[132:133], v[124:125], off offset:1024
	global_store_dwordx2 v[132:133], v[126:127], off offset:1536
	v_lshl_add_u64 v[132:133], v[132:133], 0, v[152:153]
	global_load_dwordx4 v[16:19], v[128:129], off nt
	global_load_dwordx4 v[20:23], v[128:129], off offset:1024 nt
	global_load_dwordx4 v[24:27], v[128:129], off offset:2048 nt
	global_load_dwordx4 v[28:31], v[128:129], off offset:3072 nt
	v_lshl_add_u64 v[128:129], v[128:129], 0, v[150:151]
	v_add_f32_e32 v112, v32, v33
	v_add_f32_e32 v113, v34, v35
	v_add_f32_e32 v114, v36, v37
	v_add_f32_e32 v115, v38, v39
	v_add_f32_e32 v116, v40, v41
	v_add_f32_e32 v117, v42, v43
	v_add_f32_e32 v118, v44, v45
	v_add_f32_e32 v119, v46, v47
	v_add_f32_e32 v112, v112, v116
	v_add_f32_e32 v113, v113, v117
	v_add_f32_e32 v114, v114, v118
	v_add_f32_e32 v115, v115, v119
	v_add_f32_e32 v112, v112, v113
	v_add_f32_e32 v114, v114, v115
	v_add_f32_e32 v112, v112, v114
	s_nop 1
	v_add_f32_dpp v112, v112, v112 quad_perm:[1,0,3,2] row_mask:0xf bank_mask:0xf
	s_nop 1
	v_add_f32_dpp v112, v112, v112 quad_perm:[2,3,0,1] row_mask:0xf bank_mask:0xf
	s_nop 1
	v_add_f32_dpp v112, v112, v112 row_half_mirror row_mask:0xf bank_mask:0xf
	s_nop 1
	v_add_f32_dpp v112, v112, v112 row_mirror row_mask:0xf bank_mask:0xf
	s_nop 1
	v_add_f32_dpp v112, v112, v112 row_bcast:15 row_mask:0xa bank_mask:0xf
	s_nop 1
	v_add_f32_dpp v112, v112, v112 row_bcast:31 row_mask:0xc bank_mask:0xf
	s_nop 1
	v_readlane_b32 s2, v112, 63
	s_nop 1
	v_fmac_f32_e32 v32, s2, v142
	v_fmac_f32_e32 v33, s2, v142
	v_fmac_f32_e32 v34, s2, v142
	v_fmac_f32_e32 v35, s2, v142
	v_fmac_f32_e32 v36, s2, v142
	v_fmac_f32_e32 v37, s2, v142
	v_fmac_f32_e32 v38, s2, v142
	v_fmac_f32_e32 v39, s2, v142
	v_fmac_f32_e32 v40, s2, v142
	v_fmac_f32_e32 v41, s2, v142
	v_fmac_f32_e32 v42, s2, v142
	v_fmac_f32_e32 v43, s2, v142
	v_fmac_f32_e32 v44, s2, v142
	v_fmac_f32_e32 v45, s2, v142
	v_fmac_f32_e32 v46, s2, v142
	v_fmac_f32_e32 v47, s2, v142
	v_mul_f32_e32 v112, v32, v32
	v_mul_f32_e32 v113, v33, v33
	v_mul_f32_e32 v114, v34, v34
	v_mul_f32_e32 v115, v35, v35
	v_fmac_f32_e32 v112, v36, v36
	v_fmac_f32_e32 v113, v37, v37
	v_fmac_f32_e32 v114, v38, v38
	v_fmac_f32_e32 v115, v39, v39
	v_fmac_f32_e32 v112, v40, v40
	v_fmac_f32_e32 v113, v41, v41
	v_fmac_f32_e32 v114, v42, v42
	v_fmac_f32_e32 v115, v43, v43
	v_fmac_f32_e32 v112, v44, v44
	v_fmac_f32_e32 v113, v45, v45
	v_fmac_f32_e32 v114, v46, v46
	v_fmac_f32_e32 v115, v47, v47
	v_add_f32_e32 v112, v112, v113
	v_add_f32_e32 v114, v114, v115
	v_add_f32_e32 v112, v112, v114
	s_nop 1
	v_add_f32_dpp v112, v112, v112 quad_perm:[1,0,3,2] row_mask:0xf bank_mask:0xf
	s_nop 1
	v_add_f32_dpp v112, v112, v112 quad_perm:[2,3,0,1] row_mask:0xf bank_mask:0xf
	s_nop 1
	v_add_f32_dpp v112, v112, v112 row_half_mirror row_mask:0xf bank_mask:0xf
	s_nop 1
	v_add_f32_dpp v112, v112, v112 row_mirror row_mask:0xf bank_mask:0xf
	s_nop 1
	v_add_f32_dpp v112, v112, v112 row_bcast:15 row_mask:0xa bank_mask:0xf
	s_nop 1
	v_add_f32_dpp v112, v112, v112 row_bcast:31 row_mask:0xc bank_mask:0xf
	s_nop 1
	v_readlane_b32 s2, v112, 63
	s_nop 1
	v_mov_b32_e32 v113, 0x358637bd
	v_mov_b32_e32 v114, 0x3a800000
	v_fmac_f32_e32 v113, s2, v114
	v_rsq_f32_e32 v115, v113
	v_mul_f32_e32 v113, 0.5, v113
	v_mul_f32_e32 v116, v115, v115
	v_mov_b32_e32 v117, 0x3fc00000
	v_fma_f32 v116, -v113, v116, v117
	v_mul_f32_e32 v144, v115, v116
	v_pk_mul_f32 v[32:33], v[32:33], v[144:145] op_sel_hi:[1,0]
	v_pk_mul_f32 v[34:35], v[34:35], v[144:145] op_sel_hi:[1,0]
	v_pk_mul_f32 v[36:37], v[36:37], v[144:145] op_sel_hi:[1,0]
	v_pk_mul_f32 v[38:39], v[38:39], v[144:145] op_sel_hi:[1,0]
	v_pk_mul_f32 v[40:41], v[40:41], v[144:145] op_sel_hi:[1,0]
	v_pk_mul_f32 v[42:43], v[42:43], v[144:145] op_sel_hi:[1,0]
	v_pk_mul_f32 v[44:45], v[44:45], v[144:145] op_sel_hi:[1,0]
	v_pk_mul_f32 v[46:47], v[46:47], v[144:145] op_sel_hi:[1,0]
	v_pk_fma_f32 v[32:33], v[80:81], v[32:33], v[96:97]
	v_pk_fma_f32 v[34:35], v[82:83], v[34:35], v[98:99]
	v_pk_fma_f32 v[36:37], v[84:85], v[36:37], v[100:101]
	v_pk_fma_f32 v[38:39], v[86:87], v[38:39], v[102:103]
	v_pk_fma_f32 v[40:41], v[88:89], v[40:41], v[104:105]
	v_pk_fma_f32 v[42:43], v[90:91], v[42:43], v[106:107]
	v_pk_fma_f32 v[44:45], v[92:93], v[44:45], v[108:109]
	v_pk_fma_f32 v[46:47], v[94:95], v[46:47], v[110:111]
	global_store_dwordx4 v[130:131], v[32:35], off
	global_store_dwordx4 v[130:131], v[36:39], off offset:1024
	global_store_dwordx4 v[130:131], v[40:43], off offset:2048
	global_store_dwordx4 v[130:131], v[44:47], off offset:3072
	v_lshl_add_u64 v[130:131], v[130:131], 0, v[150:151]
	v_add_f32_e32 v112, v32, v33
	v_add_f32_e32 v113, v34, v35
	v_add_f32_e32 v114, v36, v37
	v_add_f32_e32 v115, v38, v39
	v_add_f32_e32 v116, v40, v41
	v_add_f32_e32 v117, v42, v43
	v_add_f32_e32 v118, v44, v45
	v_add_f32_e32 v119, v46, v47
	v_add_f32_e32 v112, v112, v116
	v_add_f32_e32 v113, v113, v117
	v_add_f32_e32 v114, v114, v118
	v_add_f32_e32 v115, v115, v119
	v_add_f32_e32 v112, v112, v113
	v_add_f32_e32 v114, v114, v115
	v_add_f32_e32 v112, v112, v114
	s_nop 1
	v_add_f32_dpp v112, v112, v112 quad_perm:[1,0,3,2] row_mask:0xf bank_mask:0xf
	s_nop 1
	v_add_f32_dpp v112, v112, v112 quad_perm:[2,3,0,1] row_mask:0xf bank_mask:0xf
	s_nop 1
	v_add_f32_dpp v112, v112, v112 row_half_mirror row_mask:0xf bank_mask:0xf
	s_nop 1
	v_add_f32_dpp v112, v112, v112 row_mirror row_mask:0xf bank_mask:0xf
	s_nop 1
	v_add_f32_dpp v112, v112, v112 row_bcast:15 row_mask:0xa bank_mask:0xf
	s_nop 1
	v_add_f32_dpp v112, v112, v112 row_bcast:31 row_mask:0xc bank_mask:0xf
	s_nop 1
	v_readlane_b32 s2, v112, 63
	s_nop 1
	v_fmac_f32_e32 v32, s2, v142
	v_fmac_f32_e32 v33, s2, v142
	v_fmac_f32_e32 v34, s2, v142
	v_fmac_f32_e32 v35, s2, v142
	v_fmac_f32_e32 v36, s2, v142
	v_fmac_f32_e32 v37, s2, v142
	v_fmac_f32_e32 v38, s2, v142
	v_fmac_f32_e32 v39, s2, v142
	v_fmac_f32_e32 v40, s2, v142
	v_fmac_f32_e32 v41, s2, v142
	v_fmac_f32_e32 v42, s2, v142
	v_fmac_f32_e32 v43, s2, v142
	v_fmac_f32_e32 v44, s2, v142
	v_fmac_f32_e32 v45, s2, v142
	v_fmac_f32_e32 v46, s2, v142
	v_fmac_f32_e32 v47, s2, v142
	v_mul_f32_e32 v112, v32, v32
	v_mul_f32_e32 v113, v33, v33
	v_mul_f32_e32 v114, v34, v34
	v_mul_f32_e32 v115, v35, v35
	v_fmac_f32_e32 v112, v36, v36
	v_fmac_f32_e32 v113, v37, v37
	v_fmac_f32_e32 v114, v38, v38
	v_fmac_f32_e32 v115, v39, v39
	v_fmac_f32_e32 v112, v40, v40
	v_fmac_f32_e32 v113, v41, v41
	v_fmac_f32_e32 v114, v42, v42
	v_fmac_f32_e32 v115, v43, v43
	v_fmac_f32_e32 v112, v44, v44
	v_fmac_f32_e32 v113, v45, v45
	v_fmac_f32_e32 v114, v46, v46
	v_fmac_f32_e32 v115, v47, v47
	v_add_f32_e32 v112, v112, v113
	v_add_f32_e32 v114, v114, v115
	v_add_f32_e32 v112, v112, v114
	s_nop 1
	v_add_f32_dpp v112, v112, v112 quad_perm:[1,0,3,2] row_mask:0xf bank_mask:0xf
	s_nop 1
	v_add_f32_dpp v112, v112, v112 quad_perm:[2,3,0,1] row_mask:0xf bank_mask:0xf
	s_nop 1
	v_add_f32_dpp v112, v112, v112 row_half_mirror row_mask:0xf bank_mask:0xf
	s_nop 1
	v_add_f32_dpp v112, v112, v112 row_mirror row_mask:0xf bank_mask:0xf
	s_nop 1
	v_add_f32_dpp v112, v112, v112 row_bcast:15 row_mask:0xa bank_mask:0xf
	s_nop 1
	v_add_f32_dpp v112, v112, v112 row_bcast:31 row_mask:0xc bank_mask:0xf
	s_nop 1
	v_readlane_b32 s2, v112, 63
	s_nop 1
	v_mov_b32_e32 v113, 0x358637bd
	v_mov_b32_e32 v114, 0x3a800000
	v_fmac_f32_e32 v113, s2, v114
	v_rsq_f32_e32 v115, v113
	v_mul_f32_e32 v113, 0.5, v113
	v_mul_f32_e32 v116, v115, v115
	v_mov_b32_e32 v117, 0x3fc00000
	v_fma_f32 v116, -v113, v116, v117
	v_mul_f32_e32 v144, v115, v116
	v_pk_mul_f32 v[32:33], v[32:33], v[144:145] op_sel_hi:[1,0]
	v_pk_mul_f32 v[34:35], v[34:35], v[144:145] op_sel_hi:[1,0]
	v_pk_mul_f32 v[36:37], v[36:37], v[144:145] op_sel_hi:[1,0]
	v_pk_mul_f32 v[38:39], v[38:39], v[144:145] op_sel_hi:[1,0]
	v_pk_mul_f32 v[40:41], v[40:41], v[144:145] op_sel_hi:[1,0]
	v_pk_mul_f32 v[42:43], v[42:43], v[144:145] op_sel_hi:[1,0]
	v_pk_mul_f32 v[44:45], v[44:45], v[144:145] op_sel_hi:[1,0]
	v_pk_mul_f32 v[46:47], v[46:47], v[144:145] op_sel_hi:[1,0]
	v_pk_fma_f32 v[32:33], v[64:65], v[32:33], v[48:49]
	v_pk_fma_f32 v[34:35], v[66:67], v[34:35], v[50:51]
	v_pk_fma_f32 v[36:37], v[68:69], v[36:37], v[52:53]
	v_pk_fma_f32 v[38:39], v[70:71], v[38:39], v[54:55]
	v_pk_fma_f32 v[40:41], v[72:73], v[40:41], v[56:57]
	v_pk_fma_f32 v[42:43], v[74:75], v[42:43], v[58:59]
	v_pk_fma_f32 v[44:45], v[76:77], v[44:45], v[60:61]
	v_pk_fma_f32 v[46:47], v[78:79], v[46:47], v[62:63]
	v_cvt_pk_bf16_f32 v120, v32, v33
	v_cvt_pk_bf16_f32 v121, v34, v35
	v_cvt_pk_bf16_f32 v122, v36, v37
	v_cvt_pk_bf16_f32 v123, v38, v39
	v_cvt_pk_bf16_f32 v124, v40, v41
	v_cvt_pk_bf16_f32 v125, v42, v43
	v_cvt_pk_bf16_f32 v126, v44, v45
	v_cvt_pk_bf16_f32 v127, v46, v47
	global_store_dwordx2 v[132:133], v[120:121], off
	global_store_dwordx2 v[132:133], v[122:123], off offset:512
	global_store_dwordx2 v[132:133], v[124:125], off offset:1024
	global_store_dwordx2 v[132:133], v[126:127], off offset:1536
	v_lshl_add_u64 v[132:133], v[132:133], 0, v[152:153]
	s_add_i32 s0, s0, 1
	s_cmp_lt_i32 s0, 3
	s_cbranch_scc1 .Lln1a_loop
	s_branch .LBB0_438
.Lln1_layer1:
	v_readlane_b32 s2, v254, 38
	v_lshrrev_b32_e32 v146, 6, v221
	v_and_b32_e32 v112, 63, v221
	v_mov_b32_e32 v150, 0x800000
	v_mov_b32_e32 v151, 0
	v_mov_b32_e32 v152, 0x400000
	v_mov_b32_e32 v153, 0
	v_mov_b32_e32 v154, 0x3000
	v_mov_b32_e32 v155, 0
	v_add_u32_e32 v146, s2, v146
	v_lshlrev_b32_e32 v148, 4, v112
	v_mov_b32_e32 v149, 0
	v_lshl_add_u32 v140, v146, 12, v148
	v_mov_b32_e32 v141, 0
	v_mov_b32_e32 v142, 0xba800000
	s_mov_b32 s0, 0
	v_add_u32_e32 v114, 0x1c000, v148
	v_mov_b32_e32 v115, 0
	v_lshl_add_u64 v[134:135], s[60:61], 0, v[114:115]
	v_lshl_add_u64 v[128:129], s[98:99], 0, v[140:141]
	v_mov_b32_e32 v130, v128
	v_mov_b32_e32 v131, v129
	v_readlane_b32 s42, v255, 6
	s_lshl_b32 s42, s42, 12
	s_add_u32 s44, s94, s42
	s_addc_u32 s45, s95, 0
	s_add_u32 s42, s96, s42
	s_addc_u32 s43, s97, 0
	v_lshl_add_u64 v[136:137], s[44:45], 0, v[148:149]
	v_lshl_add_u64 v[138:139], s[42:43], 0, v[148:149]
	global_load_dwordx4 v[80:83], v[136:137], off
	global_load_dwordx4 v[84:87], v[136:137], off offset:1024
	global_load_dwordx4 v[88:91], v[136:137], off offset:2048
	global_load_dwordx4 v[92:95], v[136:137], off offset:3072
	global_load_dwordx4 v[96:99], v[138:139], off
	global_load_dwordx4 v[100:103], v[138:139], off offset:1024
	global_load_dwordx4 v[104:107], v[138:139], off offset:2048
	global_load_dwordx4 v[108:111], v[138:139], off offset:3072
	global_load_dwordx4 v[0:3], v[128:129], off nt
	global_load_dwordx4 v[4:7], v[128:129], off offset:1024 nt
	global_load_dwordx4 v[8:11], v[128:129], off offset:2048 nt
	global_load_dwordx4 v[12:15], v[128:129], off offset:3072 nt
	v_lshl_add_u64 v[128:129], v[128:129], 0, v[150:151]
	global_load_dword v156, v[134:135], off
	global_load_dword v156, v[134:135], off
	global_load_dword v156, v[134:135], off
	global_load_dword v156, v[134:135], off
	global_load_dwordx4 v[16:19], v[128:129], off nt
	global_load_dwordx4 v[20:23], v[128:129], off offset:1024 nt
	global_load_dwordx4 v[24:27], v[128:129], off offset:2048 nt
	global_load_dwordx4 v[28:31], v[128:129], off offset:3072 nt
	v_lshl_add_u64 v[128:129], v[128:129], 0, v[150:151]
	global_load_dword v156, v[134:135], off
	global_load_dword v156, v[134:135], off
	global_load_dword v156, v[134:135], off
	global_load_dword v156, v[134:135], off
.Lln1b_loop:
	global_load_dwordx4 v[32:35], v[128:129], off nt
	global_load_dwordx4 v[36:39], v[128:129], off offset:1024 nt
	global_load_dwordx4 v[40:43], v[128:129], off offset:2048 nt
	global_load_dwordx4 v[44:47], v[128:129], off offset:3072 nt
	v_lshl_add_u64 v[128:129], v[128:129], 0, v[150:151]
	s_waitcnt vmcnt(16)
	v_add_f32_e32 v112, v0, v1
	v_add_f32_e32 v113, v2, v3
	v_add_f32_e32 v114, v4, v5
	v_add_f32_e32 v115, v6, v7
	v_add_f32_e32 v116, v8, v9
	v_add_f32_e32 v117, v10, v11
	v_add_f32_e32 v118, v12, v13
	v_add_f32_e32 v119, v14, v15
	v_add_f32_e32 v112, v112, v116
	v_add_f32_e32 v113, v113, v117
	v_add_f32_e32 v114, v114, v118
	v_add_f32_e32 v115, v115, v119
	v_add_f32_e32 v112, v112, v113
	v_add_f32_e32 v114, v114, v115
	v_add_f32_e32 v112, v112, v114
	s_nop 1
	v_add_f32_dpp v112, v112, v112 quad_perm:[1,0,3,2] row_mask:0xf bank_mask:0xf
	s_nop 1
	v_add_f32_dpp v112, v112, v112 quad_perm:[2,3,0,1] row_mask:0xf bank_mask:0xf
	s_nop 1
	v_add_f32_dpp v112, v112, v112 row_half_mirror row_mask:0xf bank_mask:0xf
	s_nop 1
	v_add_f32_dpp v112, v112, v112 row_mirror row_mask:0xf bank_mask:0xf
	s_nop 1
	v_add_f32_dpp v112, v112, v112 row_bcast:15 row_mask:0xa bank_mask:0xf
	s_nop 1
	v_add_f32_dpp v112, v112, v112 row_bcast:31 row_mask:0xc bank_mask:0xf
	s_nop 1
	v_readlane_b32 s2, v112, 63
	s_nop 1
	v_fmac_f32_e32 v0, s2, v142
	v_fmac_f32_e32 v1, s2, v142
	v_fmac_f32_e32 v2, s2, v142
	v_fmac_f32_e32 v3, s2, v142
	v_fmac_f32_e32 v4, s2, v142
	v_fmac_f32_e32 v5, s2, v142
	v_fmac_f32_e32 v6, s2, v142
	v_fmac_f32_e32 v7, s2, v142
	v_fmac_f32_e32 v8, s2, v142
	v_fmac_f32_e32 v9, s2, v142
	v_fmac_f32_e32 v10, s2, v142
	v_fmac_f32_e32 v11, s2, v142
	v_fmac_f32_e32 v12, s2, v142
	v_fmac_f32_e32 v13, s2, v142
	v_fmac_f32_e32 v14, s2, v142
	v_fmac_f32_e32 v15, s2, v142
	v_mul_f32_e32 v112, v0, v0
	v_mul_f32_e32 v113, v1, v1
	v_mul_f32_e32 v114, v2, v2
	v_mul_f32_e32 v115, v3, v3
	v_fmac_f32_e32 v112, v4, v4
	v_fmac_f32_e32 v113, v5, v5
	v_fmac_f32_e32 v114, v6, v6
	v_fmac_f32_e32 v115, v7, v7
	v_fmac_f32_e32 v112, v8, v8
	v_fmac_f32_e32 v113, v9, v9
	v_fmac_f32_e32 v114, v10, v10
	v_fmac_f32_e32 v115, v11, v11
	v_fmac_f32_e32 v112, v12, v12
	v_fmac_f32_e32 v113, v13, v13
	v_fmac_f32_e32 v114, v14, v14
	v_fmac_f32_e32 v115, v15, v15
	v_add_f32_e32 v112, v112, v113
	v_add_f32_e32 v114, v114, v115
	v_add_f32_e32 v112, v112, v114
	s_nop 1
	v_add_f32_dpp v112, v112, v112 quad_perm:[1,0,3,2] row_mask:0xf bank_mask:0xf
	s_nop 1
	v_add_f32_dpp v112, v112, v112 quad_perm:[2,3,0,1] row_mask:0xf bank_mask:0xf
	s_nop 1
	v_add_f32_dpp v112, v112, v112 row_half_mirror row_mask:0xf bank_mask:0xf
	s_nop 1
	v_add_f32_dpp v112, v112, v112 row_mirror row_mask:0xf bank_mask:0xf
	s_nop 1
	v_add_f32_dpp v112, v112, v112 row_bcast:15 row_mask:0xa bank_mask:0xf
	s_nop 1
	v_add_f32_dpp v112, v112, v112 row_bcast:31 row_mask:0xc bank_mask:0xf
	s_nop 1
	v_readlane_b32 s2, v112, 63
	s_nop 1
	v_mov_b32_e32 v113, 0x358637bd
	v_mov_b32_e32 v114, 0x3a800000
	v_fmac_f32_e32 v113, s2, v114
	v_rsq_f32_e32 v115, v113
	v_mul_f32_e32 v113, 0.5, v113
	v_mul_f32_e32 v116, v115, v115
	v_mov_b32_e32 v117, 0x3fc00000
	v_fma_f32 v116, -v113, v116, v117
	v_mul_f32_e32 v144, v115, v116
	v_pk_mul_f32 v[0:1], v[0:1], v[144:145] op_sel_hi:[1,0]
	v_pk_mul_f32 v[2:3], v[2:3], v[144:145] op_sel_hi:[1,0]
	v_pk_mul_f32 v[4:5], v[4:5], v[144:145] op_sel_hi:[1,0]
	v_pk_mul_f32 v[6:7], v[6:7], v[144:145] op_sel_hi:[1,0]
	v_pk_mul_f32 v[8:9], v[8:9], v[144:145] op_sel_hi:[1,0]
	v_pk_mul_f32 v[10:11], v[10:11], v[144:145] op_sel_hi:[1,0]
	v_pk_mul_f32 v[12:13], v[12:13], v[144:145] op_sel_hi:[1,0]
	v_pk_mul_f32 v[14:15], v[14:15], v[144:145] op_sel_hi:[1,0]
	v_pk_fma_f32 v[0:1], v[80:81], v[0:1], v[96:97]
	v_pk_fma_f32 v[2:3], v[82:83], v[2:3], v[98:99]
	v_pk_fma_f32 v[4:5], v[84:85], v[4:5], v[100:101]
	v_pk_fma_f32 v[6:7], v[86:87], v[6:7], v[102:103]
	v_pk_fma_f32 v[8:9], v[88:89], v[8:9], v[104:105]
	v_pk_fma_f32 v[10:11], v[90:91], v[10:11], v[106:107]
	v_pk_fma_f32 v[12:13], v[92:93], v[12:13], v[108:109]
	v_pk_fma_f32 v[14:15], v[94:95], v[14:15], v[110:111]
	global_store_dwordx4 v[130:131], v[0:3], off
	global_store_dwordx4 v[130:131], v[4:7], off offset:1024
	global_store_dwordx4 v[130:131], v[8:11], off offset:2048
	global_store_dwordx4 v[130:131], v[12:15], off offset:3072
	v_lshl_add_u64 v[130:131], v[130:131], 0, v[150:151]
	global_load_dwordx4 v[0:3], v[128:129], off nt
	global_load_dwordx4 v[4:7], v[128:129], off offset:1024 nt
	global_load_dwordx4 v[8:11], v[128:129], off offset:2048 nt
	global_load_dwordx4 v[12:15], v[128:129], off offset:3072 nt
	v_lshl_add_u64 v[128:129], v[128:129], 0, v[150:151]
	s_waitcnt vmcnt(16)
	v_add_f32_e32 v112, v16, v17
	v_add_f32_e32 v113, v18, v19
	v_add_f32_e32 v114, v20, v21
	v_add_f32_e32 v115, v22, v23
	v_add_f32_e32 v116, v24, v25
	v_add_f32_e32 v117, v26, v27
	v_add_f32_e32 v118, v28, v29
	v_add_f32_e32 v119, v30, v31
	v_add_f32_e32 v112, v112, v116
	v_add_f32_e32 v113, v113, v117
	v_add_f32_e32 v114, v114, v118
	v_add_f32_e32 v115, v115, v119
	v_add_f32_e32 v112, v112, v113
	v_add_f32_e32 v114, v114, v115
	v_add_f32_e32 v112, v112, v114
	s_nop 1
	v_add_f32_dpp v112, v112, v112 quad_perm:[1,0,3,2] row_mask:0xf bank_mask:0xf
	s_nop 1
	v_add_f32_dpp v112, v112, v112 quad_perm:[2,3,0,1] row_mask:0xf bank_mask:0xf
	s_nop 1
	v_add_f32_dpp v112, v112, v112 row_half_mirror row_mask:0xf bank_mask:0xf
	s_nop 1
	v_add_f32_dpp v112, v112, v112 row_mirror row_mask:0xf bank_mask:0xf
	s_nop 1
	v_add_f32_dpp v112, v112, v112 row_bcast:15 row_mask:0xa bank_mask:0xf
	s_nop 1
	v_add_f32_dpp v112, v112, v112 row_bcast:31 row_mask:0xc bank_mask:0xf
	s_nop 1
	v_readlane_b32 s2, v112, 63
	s_nop 1
	v_fmac_f32_e32 v16, s2, v142
	v_fmac_f32_e32 v17, s2, v142
	v_fmac_f32_e32 v18, s2, v142
	v_fmac_f32_e32 v19, s2, v142
	v_fmac_f32_e32 v20, s2, v142
	v_fmac_f32_e32 v21, s2, v142
	v_fmac_f32_e32 v22, s2, v142
	v_fmac_f32_e32 v23, s2, v142
	v_fmac_f32_e32 v24, s2, v142
	v_fmac_f32_e32 v25, s2, v142
	v_fmac_f32_e32 v26, s2, v142
	v_fmac_f32_e32 v27, s2, v142
	v_fmac_f32_e32 v28, s2, v142
	v_fmac_f32_e32 v29, s2, v142
	v_fmac_f32_e32 v30, s2, v142
	v_fmac_f32_e32 v31, s2, v142
	v_mul_f32_e32 v112, v16, v16
	v_mul_f32_e32 v113, v17, v17
	v_mul_f32_e32 v114, v18, v18
	v_mul_f32_e32 v115, v19, v19
	v_fmac_f32_e32 v112, v20, v20
	v_fmac_f32_e32 v113, v21, v21
	v_fmac_f32_e32 v114, v22, v22
	v_fmac_f32_e32 v115, v23, v23
	v_fmac_f32_e32 v112, v24, v24
	v_fmac_f32_e32 v113, v25, v25
	v_fmac_f32_e32 v114, v26, v26
	v_fmac_f32_e32 v115, v27, v27
	v_fmac_f32_e32 v112, v28, v28
	v_fmac_f32_e32 v113, v29, v29
	v_fmac_f32_e32 v114, v30, v30
	v_fmac_f32_e32 v115, v31, v31
	v_add_f32_e32 v112, v112, v113
	v_add_f32_e32 v114, v114, v115
	v_add_f32_e32 v112, v112, v114
	s_nop 1
	v_add_f32_dpp v112, v112, v112 quad_perm:[1,0,3,2] row_mask:0xf bank_mask:0xf
	s_nop 1
	v_add_f32_dpp v112, v112, v112 quad_perm:[2,3,0,1] row_mask:0xf bank_mask:0xf
	s_nop 1
	v_add_f32_dpp v112, v112, v112 row_half_mirror row_mask:0xf bank_mask:0xf
	s_nop 1
	v_add_f32_dpp v112, v112, v112 row_mirror row_mask:0xf bank_mask:0xf
	s_nop 1
	v_add_f32_dpp v112, v112, v112 row_bcast:15 row_mask:0xa bank_mask:0xf
	s_nop 1
	v_add_f32_dpp v112, v112, v112 row_bcast:31 row_mask:0xc bank_mask:0xf
	s_nop 1
	v_readlane_b32 s2, v112, 63
	s_nop 1
	v_mov_b32_e32 v113, 0x358637bd
	v_mov_b32_e32 v114, 0x3a800000
	v_fmac_f32_e32 v113, s2, v114
	v_rsq_f32_e32 v115, v113
	v_mul_f32_e32 v113, 0.5, v113
	v_mul_f32_e32 v116, v115, v115
	v_mov_b32_e32 v117, 0x3fc00000
	v_fma_f32 v116, -v113, v116, v117
	v_mul_f32_e32 v144, v115, v116
	v_pk_mul_f32 v[16:17], v[16:17], v[144:145] op_sel_hi:[1,0]
	v_pk_mul_f32 v[18:19], v[18:19], v[144:145] op_sel_hi:[1,0]
	v_pk_mul_f32 v[20:21], v[20:21], v[144:145] op_sel_hi:[1,0]
	v_pk_mul_f32 v[22:23], v[22:23], v[144:145] op_sel_hi:[1,0]
	v_pk_mul_f32 v[24:25], v[24:25], v[144:145] op_sel_hi:[1,0]
	v_pk_mul_f32 v[26:27], v[26:27], v[144:145] op_sel_hi:[1,0]
	v_pk_mul_f32 v[28:29], v[28:29], v[144:145] op_sel_hi:[1,0]
	v_pk_mul_f32 v[30:31], v[30:31], v[144:145] op_sel_hi:[1,0]
	v_pk_fma_f32 v[16:17], v[80:81], v[16:17], v[96:97]
	v_pk_fma_f32 v[18:19], v[82:83], v[18:19], v[98:99]
	v_pk_fma_f32 v[20:21], v[84:85], v[20:21], v[100:101]
	v_pk_fma_f32 v[22:23], v[86:87], v[22:23], v[102:103]
	v_pk_fma_f32 v[24:25], v[88:89], v[24:25], v[104:105]
	v_pk_fma_f32 v[26:27], v[90:91], v[26:27], v[106:107]
	v_pk_fma_f32 v[28:29], v[92:93], v[28:29], v[108:109]
	v_pk_fma_f32 v[30:31], v[94:95], v[30:31], v[110:111]
	global_store_dwordx4 v[130:131], v[16:19], off
	global_store_dwordx4 v[130:131], v[20:23], off offset:1024
	global_store_dwordx4 v[130:131], v[24:27], off offset:2048
	global_store_dwordx4 v[130:131], v[28:31], off offset:3072
	v_lshl_add_u64 v[130:131], v[130:131], 0, v[150:151]
	global_load_dwordx4 v[16:19], v[128:129], off nt
	global_load_dwordx4 v[20:23], v[128:129], off offset:1024 nt
	global_load_dwordx4 v[24:27], v[128:129], off offset:2048 nt
	global_load_dwordx4 v[28:31], v[128:129], off offset:3072 nt
	v_lshl_add_u64 v[128:129], v[128:129], 0, v[150:151]
	s_waitcnt vmcnt(16)
	v_add_f32_e32 v112, v32, v33
	v_add_f32_e32 v113, v34, v35
	v_add_f32_e32 v114, v36, v37
	v_add_f32_e32 v115, v38, v39
	v_add_f32_e32 v116, v40, v41
	v_add_f32_e32 v117, v42, v43
	v_add_f32_e32 v118, v44, v45
	v_add_f32_e32 v119, v46, v47
	v_add_f32_e32 v112, v112, v116
	v_add_f32_e32 v113, v113, v117
	v_add_f32_e32 v114, v114, v118
	v_add_f32_e32 v115, v115, v119
	v_add_f32_e32 v112, v112, v113
	v_add_f32_e32 v114, v114, v115
	v_add_f32_e32 v112, v112, v114
	s_nop 1
	v_add_f32_dpp v112, v112, v112 quad_perm:[1,0,3,2] row_mask:0xf bank_mask:0xf
	s_nop 1
	v_add_f32_dpp v112, v112, v112 quad_perm:[2,3,0,1] row_mask:0xf bank_mask:0xf
	s_nop 1
	v_add_f32_dpp v112, v112, v112 row_half_mirror row_mask:0xf bank_mask:0xf
	s_nop 1
	v_add_f32_dpp v112, v112, v112 row_mirror row_mask:0xf bank_mask:0xf
	s_nop 1
	v_add_f32_dpp v112, v112, v112 row_bcast:15 row_mask:0xa bank_mask:0xf
	s_nop 1
	v_add_f32_dpp v112, v112, v112 row_bcast:31 row_mask:0xc bank_mask:0xf
	s_nop 1
	v_readlane_b32 s2, v112, 63
	s_nop 1
	v_fmac_f32_e32 v32, s2, v142
	v_fmac_f32_e32 v33, s2, v142
	v_fmac_f32_e32 v34, s2, v142
	v_fmac_f32_e32 v35, s2, v142
	v_fmac_f32_e32 v36, s2, v142
	v_fmac_f32_e32 v37, s2, v142
	v_fmac_f32_e32 v38, s2, v142
	v_fmac_f32_e32 v39, s2, v142
	v_fmac_f32_e32 v40, s2, v142
	v_fmac_f32_e32 v41, s2, v142
	v_fmac_f32_e32 v42, s2, v142
	v_fmac_f32_e32 v43, s2, v142
	v_fmac_f32_e32 v44, s2, v142
	v_fmac_f32_e32 v45, s2, v142
	v_fmac_f32_e32 v46, s2, v142
	v_fmac_f32_e32 v47, s2, v142
	v_mul_f32_e32 v112, v32, v32
	v_mul_f32_e32 v113, v33, v33
	v_mul_f32_e32 v114, v34, v34
	v_mul_f32_e32 v115, v35, v35
	v_fmac_f32_e32 v112, v36, v36
	v_fmac_f32_e32 v113, v37, v37
	v_fmac_f32_e32 v114, v38, v38
	v_fmac_f32_e32 v115, v39, v39
	v_fmac_f32_e32 v112, v40, v40
	v_fmac_f32_e32 v113, v41, v41
	v_fmac_f32_e32 v114, v42, v42
	v_fmac_f32_e32 v115, v43, v43
	v_fmac_f32_e32 v112, v44, v44
	v_fmac_f32_e32 v113, v45, v45
	v_fmac_f32_e32 v114, v46, v46
	v_fmac_f32_e32 v115, v47, v47
	v_add_f32_e32 v112, v112, v113
	v_add_f32_e32 v114, v114, v115
	v_add_f32_e32 v112, v112, v114
	s_nop 1
	v_add_f32_dpp v112, v112, v112 quad_perm:[1,0,3,2] row_mask:0xf bank_mask:0xf
	s_nop 1
	v_add_f32_dpp v112, v112, v112 quad_perm:[2,3,0,1] row_mask:0xf bank_mask:0xf
	s_nop 1
	v_add_f32_dpp v112, v112, v112 row_half_mirror row_mask:0xf bank_mask:0xf
	s_nop 1
	v_add_f32_dpp v112, v112, v112 row_mirror row_mask:0xf bank_mask:0xf
	s_nop 1
	v_add_f32_dpp v112, v112, v112 row_bcast:15 row_mask:0xa bank_mask:0xf
	s_nop 1
	v_add_f32_dpp v112, v112, v112 row_bcast:31 row_mask:0xc bank_mask:0xf
	s_nop 1
	v_readlane_b32 s2, v112, 63
	s_nop 1
	v_mov_b32_e32 v113, 0x358637bd
	v_mov_b32_e32 v114, 0x3a800000
	v_fmac_f32_e32 v113, s2, v114
	v_rsq_f32_e32 v115, v113
	v_mul_f32_e32 v113, 0.5, v113
	v_mul_f32_e32 v116, v115, v115
	v_mov_b32_e32 v117, 0x3fc00000
	v_fma_f32 v116, -v113, v116, v117
	v_mul_f32_e32 v144, v115, v116
	v_pk_mul_f32 v[32:33], v[32:33], v[144:145] op_sel_hi:[1,0]
	v_pk_mul_f32 v[34:35], v[34:35], v[144:145] op_sel_hi:[1,0]
	v_pk_mul_f32 v[36:37], v[36:37], v[144:145] op_sel_hi:[1,0]
	v_pk_mul_f32 v[38:39], v[38:39], v[144:145] op_sel_hi:[1,0]
	v_pk_mul_f32 v[40:41], v[40:41], v[144:145] op_sel_hi:[1,0]
	v_pk_mul_f32 v[42:43], v[42:43], v[144:145] op_sel_hi:[1,0]
	v_pk_mul_f32 v[44:45], v[44:45], v[144:145] op_sel_hi:[1,0]
	v_pk_mul_f32 v[46:47], v[46:47], v[144:145] op_sel_hi:[1,0]
	v_pk_fma_f32 v[32:33], v[80:81], v[32:33], v[96:97]
	v_pk_fma_f32 v[34:35], v[82:83], v[34:35], v[98:99]
	v_pk_fma_f32 v[36:37], v[84:85], v[36:37], v[100:101]
	v_pk_fma_f32 v[38:39], v[86:87], v[38:39], v[102:103]
	v_pk_fma_f32 v[40:41], v[88:89], v[40:41], v[104:105]
	v_pk_fma_f32 v[42:43], v[90:91], v[42:43], v[106:107]
	v_pk_fma_f32 v[44:45], v[92:93], v[44:45], v[108:109]
	v_pk_fma_f32 v[46:47], v[94:95], v[46:47], v[110:111]
	global_store_dwordx4 v[130:131], v[32:35], off
	global_store_dwordx4 v[130:131], v[36:39], off offset:1024
	global_store_dwordx4 v[130:131], v[40:43], off offset:2048
	global_store_dwordx4 v[130:131], v[44:47], off offset:3072
	v_lshl_add_u64 v[130:131], v[130:131], 0, v[150:151]
	global_load_dwordx4 v[32:35], v[128:129], off nt
	global_load_dwordx4 v[36:39], v[128:129], off offset:1024 nt
	global_load_dwordx4 v[40:43], v[128:129], off offset:2048 nt
	global_load_dwordx4 v[44:47], v[128:129], off offset:3072 nt
	v_lshl_add_u64 v[128:129], v[128:129], 0, v[150:151]
	s_cmp_lg_u32 s0, 2
	s_cbranch_scc1 .Lln1b_nopark
	v_lshl_add_u64 v[128:129], s[60:61], 0, v[148:149]
.Lln1b_nopark:
	s_waitcnt vmcnt(16)
	v_add_f32_e32 v112, v0, v1
	v_add_f32_e32 v113, v2, v3
	v_add_f32_e32 v114, v4, v5
	v_add_f32_e32 v115, v6, v7
	v_add_f32_e32 v116, v8, v9
	v_add_f32_e32 v117, v10, v11
	v_add_f32_e32 v118, v12, v13
	v_add_f32_e32 v119, v14, v15
	v_add_f32_e32 v112, v112, v116
	v_add_f32_e32 v113, v113, v117
	v_add_f32_e32 v114, v114, v118
	v_add_f32_e32 v115, v115, v119
	v_add_f32_e32 v112, v112, v113
	v_add_f32_e32 v114, v114, v115
	v_add_f32_e32 v112, v112, v114
	s_nop 1
	v_add_f32_dpp v112, v112, v112 quad_perm:[1,0,3,2] row_mask:0xf bank_mask:0xf
	s_nop 1
	v_add_f32_dpp v112, v112, v112 quad_perm:[2,3,0,1] row_mask:0xf bank_mask:0xf
	s_nop 1
	v_add_f32_dpp v112, v112, v112 row_half_mirror row_mask:0xf bank_mask:0xf
	s_nop 1
	v_add_f32_dpp v112, v112, v112 row_mirror row_mask:0xf bank_mask:0xf
	s_nop 1
	v_add_f32_dpp v112, v112, v112 row_bcast:15 row_mask:0xa bank_mask:0xf
	s_nop 1
	v_add_f32_dpp v112, v112, v112 row_bcast:31 row_mask:0xc bank_mask:0xf
	s_nop 1
	v_readlane_b32 s2, v112, 63
	s_nop 1
	v_fmac_f32_e32 v0, s2, v142
	v_fmac_f32_e32 v1, s2, v142
	v_fmac_f32_e32 v2, s2, v142
	v_fmac_f32_e32 v3, s2, v142
	v_fmac_f32_e32 v4, s2, v142
	v_fmac_f32_e32 v5, s2, v142
	v_fmac_f32_e32 v6, s2, v142
	v_fmac_f32_e32 v7, s2, v142
	v_fmac_f32_e32 v8, s2, v142
	v_fmac_f32_e32 v9, s2, v142
	v_fmac_f32_e32 v10, s2, v142
	v_fmac_f32_e32 v11, s2, v142
	v_fmac_f32_e32 v12, s2, v142
	v_fmac_f32_e32 v13, s2, v142
	v_fmac_f32_e32 v14, s2, v142
	v_fmac_f32_e32 v15, s2, v142
	v_mul_f32_e32 v112, v0, v0
	v_mul_f32_e32 v113, v1, v1
	v_mul_f32_e32 v114, v2, v2
	v_mul_f32_e32 v115, v3, v3
	v_fmac_f32_e32 v112, v4, v4
	v_fmac_f32_e32 v113, v5, v5
	v_fmac_f32_e32 v114, v6, v6
	v_fmac_f32_e32 v115, v7, v7
	v_fmac_f32_e32 v112, v8, v8
	v_fmac_f32_e32 v113, v9, v9
	v_fmac_f32_e32 v114, v10, v10
	v_fmac_f32_e32 v115, v11, v11
	v_fmac_f32_e32 v112, v12, v12
	v_fmac_f32_e32 v113, v13, v13
	v_fmac_f32_e32 v114, v14, v14
	v_fmac_f32_e32 v115, v15, v15
	v_add_f32_e32 v112, v112, v113
	v_add_f32_e32 v114, v114, v115
	v_add_f32_e32 v112, v112, v114
	s_nop 1
	v_add_f32_dpp v112, v112, v112 quad_perm:[1,0,3,2] row_mask:0xf bank_mask:0xf
	s_nop 1
	v_add_f32_dpp v112, v112, v112 quad_perm:[2,3,0,1] row_mask:0xf bank_mask:0xf
	s_nop 1
	v_add_f32_dpp v112, v112, v112 row_half_mirror row_mask:0xf bank_mask:0xf
	s_nop 1
	v_add_f32_dpp v112, v112, v112 row_mirror row_mask:0xf bank_mask:0xf
	s_nop 1
	v_add_f32_dpp v112, v112, v112 row_bcast:15 row_mask:0xa bank_mask:0xf
	s_nop 1
	v_add_f32_dpp v112, v112, v112 row_bcast:31 row_mask:0xc bank_mask:0xf
	s_nop 1
	v_readlane_b32 s2, v112, 63
	s_nop 1
	v_mov_b32_e32 v113, 0x358637bd
	v_mov_b32_e32 v114, 0x3a800000
	v_fmac_f32_e32 v113, s2, v114
	v_rsq_f32_e32 v115, v113
	v_mul_f32_e32 v113, 0.5, v113
	v_mul_f32_e32 v116, v115, v115
	v_mov_b32_e32 v117, 0x3fc00000
	v_fma_f32 v116, -v113, v116, v117
	v_mul_f32_e32 v144, v115, v116
	v_pk_mul_f32 v[0:1], v[0:1], v[144:145] op_sel_hi:[1,0]
	v_pk_mul_f32 v[2:3], v[2:3], v[144:145] op_sel_hi:[1,0]
	v_pk_mul_f32 v[4:5], v[4:5], v[144:145] op_sel_hi:[1,0]
	v_pk_mul_f32 v[6:7], v[6:7], v[144:145] op_sel_hi:[1,0]
	v_pk_mul_f32 v[8:9], v[8:9], v[144:145] op_sel_hi:[1,0]
	v_pk_mul_f32 v[10:11], v[10:11], v[144:145] op_sel_hi:[1,0]
	v_pk_mul_f32 v[12:13], v[12:13], v[144:145] op_sel_hi:[1,0]
	v_pk_mul_f32 v[14:15], v[14:15], v[144:145] op_sel_hi:[1,0]
	v_pk_fma_f32 v[0:1], v[80:81], v[0:1], v[96:97]
	v_pk_fma_f32 v[2:3], v[82:83], v[2:3], v[98:99]
	v_pk_fma_f32 v[4:5], v[84:85], v[4:5], v[100:101]
	v_pk_fma_f32 v[6:7], v[86:87], v[6:7], v[102:103]
	v_pk_fma_f32 v[8:9], v[88:89], v[8:9], v[104:105]
	v_pk_fma_f32 v[10:11], v[90:91], v[10:11], v[106:107]
	v_pk_fma_f32 v[12:13], v[92:93], v[12:13], v[108:109]
	v_pk_fma_f32 v[14:15], v[94:95], v[14:15], v[110:111]
	global_store_dwordx4 v[130:131], v[0:3], off
	global_store_dwordx4 v[130:131], v[4:7], off offset:1024
	global_store_dwordx4 v[130:131], v[8:11], off offset:2048
	global_store_dwordx4 v[130:131], v[12:15], off offset:3072
	v_lshl_add_u64 v[130:131], v[130:131], 0, v[150:151]
	global_load_dwordx4 v[0:3], v[128:129], off nt
	global_load_dwordx4 v[4:7], v[128:129], off offset:1024 nt
	global_load_dwordx4 v[8:11], v[128:129], off offset:2048 nt
	global_load_dwordx4 v[12:15], v[128:129], off offset:3072 nt
	v_lshl_add_u64 v[128:129], v[128:129], 0, v[150:151]
	s_waitcnt vmcnt(16)
	v_add_f32_e32 v112, v16, v17
	v_add_f32_e32 v113, v18, v19
	v_add_f32_e32 v114, v20, v21
	v_add_f32_e32 v115, v22, v23
	v_add_f32_e32 v116, v24, v25
	v_add_f32_e32 v117, v26, v27
	v_add_f32_e32 v118, v28, v29
	v_add_f32_e32 v119, v30, v31
	v_add_f32_e32 v112, v112, v116
	v_add_f32_e32 v113, v113, v117
	v_add_f32_e32 v114, v114, v118
	v_add_f32_e32 v115, v115, v119
	v_add_f32_e32 v112, v112, v113
	v_add_f32_e32 v114, v114, v115
	v_add_f32_e32 v112, v112, v114
	s_nop 1
	v_add_f32_dpp v112, v112, v112 quad_perm:[1,0,3,2] row_mask:0xf bank_mask:0xf
	s_nop 1
	v_add_f32_dpp v112, v112, v112 quad_perm:[2,3,0,1] row_mask:0xf bank_mask:0xf
	s_nop 1
	v_add_f32_dpp v112, v112, v112 row_half_mirror row_mask:0xf bank_mask:0xf
	s_nop 1
	v_add_f32_dpp v112, v112, v112 row_mirror row_mask:0xf bank_mask:0xf
	s_nop 1
	v_add_f32_dpp v112, v112, v112 row_bcast:15 row_mask:0xa bank_mask:0xf
	s_nop 1
	v_add_f32_dpp v112, v112, v112 row_bcast:31 row_mask:0xc bank_mask:0xf
	s_nop 1
	v_readlane_b32 s2, v112, 63
	s_nop 1
	v_fmac_f32_e32 v16, s2, v142
	v_fmac_f32_e32 v17, s2, v142
	v_fmac_f32_e32 v18, s2, v142
	v_fmac_f32_e32 v19, s2, v142
	v_fmac_f32_e32 v20, s2, v142
	v_fmac_f32_e32 v21, s2, v142
	v_fmac_f32_e32 v22, s2, v142
	v_fmac_f32_e32 v23, s2, v142
	v_fmac_f32_e32 v24, s2, v142
	v_fmac_f32_e32 v25, s2, v142
	v_fmac_f32_e32 v26, s2, v142
	v_fmac_f32_e32 v27, s2, v142
	v_fmac_f32_e32 v28, s2, v142
	v_fmac_f32_e32 v29, s2, v142
	v_fmac_f32_e32 v30, s2, v142
	v_fmac_f32_e32 v31, s2, v142
	v_mul_f32_e32 v112, v16, v16
	v_mul_f32_e32 v113, v17, v17
	v_mul_f32_e32 v114, v18, v18
	v_mul_f32_e32 v115, v19, v19
	v_fmac_f32_e32 v112, v20, v20
	v_fmac_f32_e32 v113, v21, v21
	v_fmac_f32_e32 v114, v22, v22
	v_fmac_f32_e32 v115, v23, v23
	v_fmac_f32_e32 v112, v24, v24
	v_fmac_f32_e32 v113, v25, v25
	v_fmac_f32_e32 v114, v26, v26
	v_fmac_f32_e32 v115, v27, v27
	v_fmac_f32_e32 v112, v28, v28
	v_fmac_f32_e32 v113, v29, v29
	v_fmac_f32_e32 v114, v30, v30
	v_fmac_f32_e32 v115, v31, v31
	v_add_f32_e32 v112, v112, v113
	v_add_f32_e32 v114, v114, v115
	v_add_f32_e32 v112, v112, v114
	s_nop 1
	v_add_f32_dpp v112, v112, v112 quad_perm:[1,0,3,2] row_mask:0xf bank_mask:0xf
	s_nop 1
	v_add_f32_dpp v112, v112, v112 quad_perm:[2,3,0,1] row_mask:0xf bank_mask:0xf
	s_nop 1
	v_add_f32_dpp v112, v112, v112 row_half_mirror row_mask:0xf bank_mask:0xf
	s_nop 1
	v_add_f32_dpp v112, v112, v112 row_mirror row_mask:0xf bank_mask:0xf
	s_nop 1
	v_add_f32_dpp v112, v112, v112 row_bcast:15 row_mask:0xa bank_mask:0xf
	s_nop 1
	v_add_f32_dpp v112, v112, v112 row_bcast:31 row_mask:0xc bank_mask:0xf
	s_nop 1
	v_readlane_b32 s2, v112, 63
	s_nop 1
	v_mov_b32_e32 v113, 0x358637bd
	v_mov_b32_e32 v114, 0x3a800000
	v_fmac_f32_e32 v113, s2, v114
	v_rsq_f32_e32 v115, v113
	v_mul_f32_e32 v113, 0.5, v113
	v_mul_f32_e32 v116, v115, v115
	v_mov_b32_e32 v117, 0x3fc00000
	v_fma_f32 v116, -v113, v116, v117
	v_mul_f32_e32 v144, v115, v116
	v_pk_mul_f32 v[16:17], v[16:17], v[144:145] op_sel_hi:[1,0]
	v_pk_mul_f32 v[18:19], v[18:19], v[144:145] op_sel_hi:[1,0]
	v_pk_mul_f32 v[20:21], v[20:21], v[144:145] op_sel_hi:[1,0]
	v_pk_mul_f32 v[22:23], v[22:23], v[144:145] op_sel_hi:[1,0]
	v_pk_mul_f32 v[24:25], v[24:25], v[144:145] op_sel_hi:[1,0]
	v_pk_mul_f32 v[26:27], v[26:27], v[144:145] op_sel_hi:[1,0]
	v_pk_mul_f32 v[28:29], v[28:29], v[144:145] op_sel_hi:[1,0]
	v_pk_mul_f32 v[30:31], v[30:31], v[144:145] op_sel_hi:[1,0]
	v_pk_fma_f32 v[16:17], v[80:81], v[16:17], v[96:97]
	v_pk_fma_f32 v[18:19], v[82:83], v[18:19], v[98:99]
	v_pk_fma_f32 v[20:21], v[84:85], v[20:21], v[100:101]
	v_pk_fma_f32 v[22:23], v[86:87], v[22:23], v[102:103]
	v_pk_fma_f32 v[24:25], v[88:89], v[24:25], v[104:105]
	v_pk_fma_f32 v[26:27], v[90:91], v[26:27], v[106:107]
	v_pk_fma_f32 v[28:29], v[92:93], v[28:29], v[108:109]
	v_pk_fma_f32 v[30:31], v[94:95], v[30:31], v[110:111]
	global_store_dwordx4 v[130:131], v[16:19], off
	global_store_dwordx4 v[130:131], v[20:23], off offset:1024
	global_store_dwordx4 v[130:131], v[24:27], off offset:2048
	global_store_dwordx4 v[130:131], v[28:31], off offset:3072
	v_lshl_add_u64 v[130:131], v[130:131], 0, v[150:151]
	global_load_dwordx4 v[16:19], v[128:129], off nt
	global_load_dwordx4 v[20:23], v[128:129], off offset:1024 nt
	global_load_dwordx4 v[24:27], v[128:129], off offset:2048 nt
	global_load_dwordx4 v[28:31], v[128:129], off offset:3072 nt
	v_lshl_add_u64 v[128:129], v[128:129], 0, v[150:151]
	s_waitcnt vmcnt(16)
	v_add_f32_e32 v112, v32, v33
	v_add_f32_e32 v113, v34, v35
	v_add_f32_e32 v114, v36, v37
	v_add_f32_e32 v115, v38, v39
	v_add_f32_e32 v116, v40, v41
	v_add_f32_e32 v117, v42, v43
	v_add_f32_e32 v118, v44, v45
	v_add_f32_e32 v119, v46, v47
	v_add_f32_e32 v112, v112, v116
	v_add_f32_e32 v113, v113, v117
	v_add_f32_e32 v114, v114, v118
	v_add_f32_e32 v115, v115, v119
	v_add_f32_e32 v112, v112, v113
	v_add_f32_e32 v114, v114, v115
	v_add_f32_e32 v112, v112, v114
	s_nop 1
	v_add_f32_dpp v112, v112, v112 quad_perm:[1,0,3,2] row_mask:0xf bank_mask:0xf
	s_nop 1
	v_add_f32_dpp v112, v112, v112 quad_perm:[2,3,0,1] row_mask:0xf bank_mask:0xf
	s_nop 1
	v_add_f32_dpp v112, v112, v112 row_half_mirror row_mask:0xf bank_mask:0xf
	s_nop 1
	v_add_f32_dpp v112, v112, v112 row_mirror row_mask:0xf bank_mask:0xf
	s_nop 1
	v_add_f32_dpp v112, v112, v112 row_bcast:15 row_mask:0xa bank_mask:0xf
	s_nop 1
	v_add_f32_dpp v112, v112, v112 row_bcast:31 row_mask:0xc bank_mask:0xf
	s_nop 1
	v_readlane_b32 s2, v112, 63
	s_nop 1
	v_fmac_f32_e32 v32, s2, v142
	v_fmac_f32_e32 v33, s2, v142
	v_fmac_f32_e32 v34, s2, v142
	v_fmac_f32_e32 v35, s2, v142
	v_fmac_f32_e32 v36, s2, v142
	v_fmac_f32_e32 v37, s2, v142
	v_fmac_f32_e32 v38, s2, v142
	v_fmac_f32_e32 v39, s2, v142
	v_fmac_f32_e32 v40, s2, v142
	v_fmac_f32_e32 v41, s2, v142
	v_fmac_f32_e32 v42, s2, v142
	v_fmac_f32_e32 v43, s2, v142
	v_fmac_f32_e32 v44, s2, v142
	v_fmac_f32_e32 v45, s2, v142
	v_fmac_f32_e32 v46, s2, v142
	v_fmac_f32_e32 v47, s2, v142
	v_mul_f32_e32 v112, v32, v32
	v_mul_f32_e32 v113, v33, v33
	v_mul_f32_e32 v114, v34, v34
	v_mul_f32_e32 v115, v35, v35
	v_fmac_f32_e32 v112, v36, v36
	v_fmac_f32_e32 v113, v37, v37
	v_fmac_f32_e32 v114, v38, v38
	v_fmac_f32_e32 v115, v39, v39
	v_fmac_f32_e32 v112, v40, v40
	v_fmac_f32_e32 v113, v41, v41
	v_fmac_f32_e32 v114, v42, v42
	v_fmac_f32_e32 v115, v43, v43
	v_fmac_f32_e32 v112, v44, v44
	v_fmac_f32_e32 v113, v45, v45
	v_fmac_f32_e32 v114, v46, v46
	v_fmac_f32_e32 v115, v47, v47
	v_add_f32_e32 v112, v112, v113
	v_add_f32_e32 v114, v114, v115
	v_add_f32_e32 v112, v112, v114
	s_nop 1
	v_add_f32_dpp v112, v112, v112 quad_perm:[1,0,3,2] row_mask:0xf bank_mask:0xf
	s_nop 1
	v_add_f32_dpp v112, v112, v112 quad_perm:[2,3,0,1] row_mask:0xf bank_mask:0xf
	s_nop 1
	v_add_f32_dpp v112, v112, v112 row_half_mirror row_mask:0xf bank_mask:0xf
	s_nop 1
	v_add_f32_dpp v112, v112, v112 row_mirror row_mask:0xf bank_mask:0xf
	s_nop 1
	v_add_f32_dpp v112, v112, v112 row_bcast:15 row_mask:0xa bank_mask:0xf
	s_nop 1
	v_add_f32_dpp v112, v112, v112 row_bcast:31 row_mask:0xc bank_mask:0xf
	s_nop 1
	v_readlane_b32 s2, v112, 63
	s_nop 1
	v_mov_b32_e32 v113, 0x358637bd
	v_mov_b32_e32 v114, 0x3a800000
	v_fmac_f32_e32 v113, s2, v114
	v_rsq_f32_e32 v115, v113
	v_mul_f32_e32 v113, 0.5, v113
	v_mul_f32_e32 v116, v115, v115
	v_mov_b32_e32 v117, 0x3fc00000
	v_fma_f32 v116, -v113, v116, v117
	v_mul_f32_e32 v144, v115, v116
	v_pk_mul_f32 v[32:33], v[32:33], v[144:145] op_sel_hi:[1,0]
	v_pk_mul_f32 v[34:35], v[34:35], v[144:145] op_sel_hi:[1,0]
	v_pk_mul_f32 v[36:37], v[36:37], v[144:145] op_sel_hi:[1,0]
	v_pk_mul_f32 v[38:39], v[38:39], v[144:145] op_sel_hi:[1,0]
	v_pk_mul_f32 v[40:41], v[40:41], v[144:145] op_sel_hi:[1,0]
	v_pk_mul_f32 v[42:43], v[42:43], v[144:145] op_sel_hi:[1,0]
	v_pk_mul_f32 v[44:45], v[44:45], v[144:145] op_sel_hi:[1,0]
	v_pk_mul_f32 v[46:47], v[46:47], v[144:145] op_sel_hi:[1,0]
	v_pk_fma_f32 v[32:33], v[80:81], v[32:33], v[96:97]
	v_pk_fma_f32 v[34:35], v[82:83], v[34:35], v[98:99]
	v_pk_fma_f32 v[36:37], v[84:85], v[36:37], v[100:101]
	v_pk_fma_f32 v[38:39], v[86:87], v[38:39], v[102:103]
	v_pk_fma_f32 v[40:41], v[88:89], v[40:41], v[104:105]
	v_pk_fma_f32 v[42:43], v[90:91], v[42:43], v[106:107]
	v_pk_fma_f32 v[44:45], v[92:93], v[44:45], v[108:109]
	v_pk_fma_f32 v[46:47], v[94:95], v[46:47], v[110:111]
	global_store_dwordx4 v[130:131], v[32:35], off
	global_store_dwordx4 v[130:131], v[36:39], off offset:1024
	global_store_dwordx4 v[130:131], v[40:43], off offset:2048
	global_store_dwordx4 v[130:131], v[44:47], off offset:3072
	v_lshl_add_u64 v[130:131], v[130:131], 0, v[150:151]
	s_add_i32 s0, s0, 1
	s_cmp_lt_i32 s0, 3
	s_cbranch_scc1 .Lln1b_loop
.LBB0_438:
	v_readlane_b32 s48, v255, 4
	s_mov_b64 s[0:1], 0
	v_readlane_b32 s49, v255, 5
